# all P0 output stores (XB8, rope tables, transposed w_in) write-through (sc1) so the grid.sync's L2 write-back at seam 0 finds nothing dirty; on top of v89
# baseline (speedup 1.0000x reference)
; __device__ __forceinline__ unsigned cvt_pk_bf16(float lo, float hi) { unsigned r; asm volatile("v_cvt_pk_bf16_f32 %0, %1, %2" : "=v"(r) : "v"(lo), "v"(hi)); return r; }
; __global__ void __launch_bounds__(512, 2) hybrid_fwd(Args a) {
;     ...
;     if (bx == 0 && tid < 72) __hip_atomic_store((unsigned*)(ws + WS_CTL) + 1024 * (tid / 9) + 64 * (tid % 9), 0u, __ATOMIC_RELAXED, __HIP_MEMORY_SCOPE_AGENT);
;     {
;         const size_t gt = (size_t)bx * 512 + tid, GT = (size_t)G * 512;
;         {
;             const size_t NCH = (size_t)M * D / 8;
;             for (size_t i0 = gt; i0 < NCH; i0 += 4 * GT) {
;                 f32x4 v[4][2];
; #pragma unroll
;                 for (int u = 0; u < 4; ++u) { const size_t i = i0 + (size_t)u * GT; if (i < NCH) { v[u][0] = ((const f32x4*)a.x)[2 * i]; v[u][1] = ((const f32x4*)a.x)[2 * i + 1]; } }
; #pragma unroll
;                 for (int u = 0; u < 4; ++u) { const size_t i = i0 + (size_t)u * GT; if (i < NCH) {
;                     u32x4 w; w.x = cvt_pk_bf16(v[u][0][0], v[u][0][1]); w.y = cvt_pk_bf16(v[u][0][2], v[u][0][3]); w.z = cvt_pk_bf16(v[u][1][0], v[u][1][1]); w.w = cvt_pk_bf16(v[u][1][2], v[u][1][3]);
;                     if (a.n_bf16 > 0) ((u32x4*)XB)[i] = w;
;                     const unsigned p0 = pack_fp8x4(v[u][0][0], v[u][0][1], v[u][0][2], v[u][0][3]), p1 = pack_fp8x4(v[u][1][0], v[u][1][1], v[u][1][2], v[u][1][3]);
;                     ((u32x2*)XB8)[i] = (u32x2){p0, p1}; } }
.LBB0_2:
	s_or_b64 exec, exec, s[4:5]
	v_cmp_eq_u32_e32 vcc, 0, v160
	s_and_saveexec_b64 s[4:5], vcc
	s_lshl_b32 s100, s2, 12
	s_add_u32 s100, s100, 0x8e10000
	v_mov_b32_e32 v243, s100
	v_mov_b32_e32 v244, 0
	s_waitcnt lgkmcnt(0)
	global_store_dword v243, v244, s[90:91] sc1
	s_getreg_b32 s100, hwreg(HW_REG_XCC_ID, 0, 4)
	v_mov_b32_e32 v244, s100
	s_lshl_b32 s100, s2, 2
	s_add_u32 s100, s100, 0x8e08000
	v_mov_b32_e32 v243, s100
	global_store_dword v243, v244, s[90:91] sc1
	s_or_b64 exec, exec, s[4:5]
	s_ashr_i32 s3, s2, 31
	s_lshl_b64 s[4:5], s[2:3], 9
	v_mov_b32_e32 v161, 0
	v_lshl_add_u64 v[38:39], s[4:5], 0, v[160:161]
	s_waitcnt lgkmcnt(0)
	s_ashr_i32 s93, s92, 31
	s_mov_b64 s[12:13], 0x400000
	s_lshl_b64 s[14:15], s[92:93], 9
	v_cmp_gt_u64_e32 vcc, s[12:13], v[38:39]
	v_lshlrev_b32_e32 v40, 3, v160
	s_mov_b32 s100, 0
	s_cmp_lg_u32 s92, 0x100
	s_cbranch_scc1 .Lp0_done
	s_load_dword s16, s[70:71], 0x1c0
	s_load_dwordx2 s[18:19], s[70:71], 0x1c8
	s_load_dwordx2 s[6:7], s[70:71], 0x0
	s_load_dwordx2 s[20:21], s[70:71], 0x8
	s_load_dwordx2 s[22:23], s[70:71], 0x10
	s_waitcnt lgkmcnt(0)
	s_cmp_lg_u32 s16, 0
	s_cbranch_scc1 .Lp0_done
	s_cmp_lg_u32 s18, -1
	s_cbranch_scc1 .Lp0_done
	s_cmpk_lg_u32 s19, 0x1fff
	s_cbranch_scc1 .Lp0_done
	v_lshl_add_u32 v1, s2, 9, v160
	v_and_b32_e32 v4, 63, v160
	v_lshlrev_b32_e32 v2, 5, v1
	v_lshlrev_b32_e32 v3, 3, v1
	s_mov_b64 s[8:9], s[88:89]
	global_load_dwordx4 v[64:67], v2, s[6:7] nt
	global_load_dwordx4 v[68:71], v2, s[6:7] offset:16 nt
	s_add_u32 s6, s6, 0x400000
	s_addc_u32 s7, s7, 0
	global_load_dwordx4 v[72:75], v2, s[6:7] nt
	global_load_dwordx4 v[76:79], v2, s[6:7] offset:16 nt
	s_add_u32 s6, s6, 0x400000
	s_addc_u32 s7, s7, 0
	global_load_dwordx4 v[80:83], v2, s[6:7] nt
	global_load_dwordx4 v[84:87], v2, s[6:7] offset:16 nt
	s_add_u32 s6, s6, 0x400000
	s_addc_u32 s7, s7, 0
	global_load_dwordx4 v[88:91], v2, s[6:7] nt
	global_load_dwordx4 v[92:95], v2, s[6:7] offset:16 nt
	s_add_u32 s6, s6, 0x400000
	s_addc_u32 s7, s7, 0
	global_load_dwordx4 v[96:99], v2, s[6:7] nt
	global_load_dwordx4 v[100:103], v2, s[6:7] offset:16 nt
	s_add_u32 s6, s6, 0x400000
	s_addc_u32 s7, s7, 0
	global_load_dwordx4 v[104:107], v2, s[6:7] nt
	global_load_dwordx4 v[108:111], v2, s[6:7] offset:16 nt
	s_add_u32 s6, s6, 0x400000
	s_addc_u32 s7, s7, 0
	global_load_dwordx4 v[112:115], v2, s[6:7] nt
	global_load_dwordx4 v[116:119], v2, s[6:7] offset:16 nt
	s_add_u32 s6, s6, 0x400000
	s_addc_u32 s7, s7, 0
	global_load_dwordx4 v[120:123], v2, s[6:7] nt
	global_load_dwordx4 v[124:127], v2, s[6:7] offset:16 nt
	s_add_u32 s6, s6, 0x400000
	s_addc_u32 s7, s7, 0
	s_waitcnt vmcnt(14)
	v_cvt_pk_fp8_f32 v8, v64, v65
	v_cvt_pk_fp8_f32 v9, v66, v67
	v_cvt_pk_fp8_f32 v10, v68, v69
	v_cvt_pk_fp8_f32 v11, v70, v71
	v_and_b32_e32 v8, 0xffff, v8
	v_and_b32_e32 v10, 0xffff, v10
	v_lshl_or_b32 v128, v9, 16, v8
	v_lshl_or_b32 v129, v11, 16, v10
	global_store_dwordx2 v3, v[128:129], s[8:9] sc1
	s_add_u32 s8, s8, 0x100000
	s_addc_u32 s9, s9, 0
	global_load_dwordx4 v[64:67], v2, s[6:7] nt
	global_load_dwordx4 v[68:71], v2, s[6:7] offset:16 nt
	s_add_u32 s6, s6, 0x400000
	s_addc_u32 s7, s7, 0
	s_waitcnt vmcnt(15)
	v_cvt_pk_fp8_f32 v8, v72, v73
	v_cvt_pk_fp8_f32 v9, v74, v75
	v_cvt_pk_fp8_f32 v10, v76, v77
	v_cvt_pk_fp8_f32 v11, v78, v79
	v_and_b32_e32 v8, 0xffff, v8
	v_and_b32_e32 v10, 0xffff, v10
	v_lshl_or_b32 v130, v9, 16, v8
	v_lshl_or_b32 v131, v11, 16, v10
	global_store_dwordx2 v3, v[130:131], s[8:9] sc1
	s_add_u32 s8, s8, 0x100000
	s_addc_u32 s9, s9, 0
	global_load_dwordx4 v[72:75], v2, s[6:7] nt
	global_load_dwordx4 v[76:79], v2, s[6:7] offset:16 nt
	s_add_u32 s6, s6, 0x400000
	s_addc_u32 s7, s7, 0
	s_waitcnt vmcnt(16)
	v_cvt_pk_fp8_f32 v8, v80, v81
	v_cvt_pk_fp8_f32 v9, v82, v83
	v_cvt_pk_fp8_f32 v10, v84, v85
	v_cvt_pk_fp8_f32 v11, v86, v87
	v_and_b32_e32 v8, 0xffff, v8
	v_and_b32_e32 v10, 0xffff, v10
	v_lshl_or_b32 v132, v9, 16, v8
	v_lshl_or_b32 v133, v11, 16, v10
	global_store_dwordx2 v3, v[132:133], s[8:9] sc1
	s_add_u32 s8, s8, 0x100000
	s_addc_u32 s9, s9, 0
	global_load_dwordx4 v[80:83], v2, s[6:7] nt
	global_load_dwordx4 v[84:87], v2, s[6:7] offset:16 nt
	s_add_u32 s6, s6, 0x400000
	s_addc_u32 s7, s7, 0
	s_waitcnt vmcnt(17)
	v_cvt_pk_fp8_f32 v8, v88, v89
	v_cvt_pk_fp8_f32 v9, v90, v91
	v_cvt_pk_fp8_f32 v10, v92, v93
	v_cvt_pk_fp8_f32 v11, v94, v95
	v_and_b32_e32 v8, 0xffff, v8
	v_and_b32_e32 v10, 0xffff, v10
	v_lshl_or_b32 v134, v9, 16, v8
	v_lshl_or_b32 v135, v11, 16, v10
	global_store_dwordx2 v3, v[134:135], s[8:9] sc1
	s_add_u32 s8, s8, 0x100000
	s_addc_u32 s9, s9, 0
	global_load_dwordx4 v[88:91], v2, s[6:7] nt
	global_load_dwordx4 v[92:95], v2, s[6:7] offset:16 nt
	s_add_u32 s6, s6, 0x400000
	s_addc_u32 s7, s7, 0
	s_waitcnt vmcnt(18)
	v_cvt_pk_fp8_f32 v8, v96, v97
	v_cvt_pk_fp8_f32 v9, v98, v99
	v_cvt_pk_fp8_f32 v10, v100, v101
	v_cvt_pk_fp8_f32 v11, v102, v103
	v_and_b32_e32 v8, 0xffff, v8
	v_and_b32_e32 v10, 0xffff, v10
	v_lshl_or_b32 v136, v9, 16, v8
	v_lshl_or_b32 v137, v11, 16, v10
	global_store_dwordx2 v3, v[136:137], s[8:9] sc1
	s_add_u32 s8, s8, 0x100000
	s_addc_u32 s9, s9, 0
	global_load_dwordx4 v[96:99], v2, s[6:7] nt
	global_load_dwordx4 v[100:103], v2, s[6:7] offset:16 nt
	s_add_u32 s6, s6, 0x400000
	s_addc_u32 s7, s7, 0
	s_waitcnt vmcnt(19)
	v_cvt_pk_fp8_f32 v8, v104, v105
	v_cvt_pk_fp8_f32 v9, v106, v107
	v_cvt_pk_fp8_f32 v10, v108, v109
	v_cvt_pk_fp8_f32 v11, v110, v111
	v_and_b32_e32 v8, 0xffff, v8
	v_and_b32_e32 v10, 0xffff, v10
	v_lshl_or_b32 v138, v9, 16, v8
	v_lshl_or_b32 v139, v11, 16, v10
	global_store_dwordx2 v3, v[138:139], s[8:9] sc1
	s_add_u32 s8, s8, 0x100000
	s_addc_u32 s9, s9, 0
	global_load_dwordx4 v[104:107], v2, s[6:7] nt
	global_load_dwordx4 v[108:111], v2, s[6:7] offset:16 nt
	s_add_u32 s6, s6, 0x400000
	s_addc_u32 s7, s7, 0
	s_waitcnt vmcnt(20)
; __device__ __forceinline__ unsigned cvt_pk_bf16(float lo, float hi) { unsigned r; asm volatile("v_cvt_pk_bf16_f32 %0, %1, %2" : "=v"(r) : "v"(lo), "v"(hi)); return r; }
; __global__ void __launch_bounds__(512, 2) hybrid_fwd(Args a) {
;     ...
;             for (size_t i0 = gt; i0 < NCH; i0 += 4 * GT) {
;                 f32x4 v[4][2];
; #pragma unroll
;                 for (int u = 0; u < 4; ++u) { const size_t i = i0 + (size_t)u * GT; if (i < NCH) { v[u][0] = ((const f32x4*)a.x)[2 * i]; v[u][1] = ((const f32x4*)a.x)[2 * i + 1]; } }
; #pragma unroll
;                 for (int u = 0; u < 4; ++u) { const size_t i = i0 + (size_t)u * GT; if (i < NCH) {
;                     u32x4 w; w.x = cvt_pk_bf16(v[u][0][0], v[u][0][1]); w.y = cvt_pk_bf16(v[u][0][2], v[u][0][3]); w.z = cvt_pk_bf16(v[u][1][0], v[u][1][1]); w.w = cvt_pk_bf16(v[u][1][2], v[u][1][3]);
;                     if (a.n_bf16 > 0) ((u32x4*)XB)[i] = w;
;                     const unsigned p0 = pack_fp8x4(v[u][0][0], v[u][0][1], v[u][0][2], v[u][0][3]), p1 = pack_fp8x4(v[u][1][0], v[u][1][1], v[u][1][2], v[u][1][3]);
;                     ((u32x2*)XB8)[i] = (u32x2){p0, p1}; } }
	v_cvt_pk_fp8_f32 v8, v112, v113
	v_cvt_pk_fp8_f32 v9, v114, v115
	v_cvt_pk_fp8_f32 v10, v116, v117
	v_cvt_pk_fp8_f32 v11, v118, v119
	v_and_b32_e32 v8, 0xffff, v8
	v_and_b32_e32 v10, 0xffff, v10
	v_lshl_or_b32 v140, v9, 16, v8
	v_lshl_or_b32 v141, v11, 16, v10
	global_store_dwordx2 v3, v[140:141], s[8:9] sc1
	s_add_u32 s8, s8, 0x100000
	s_addc_u32 s9, s9, 0
	global_load_dwordx4 v[112:115], v2, s[6:7] nt
	global_load_dwordx4 v[116:119], v2, s[6:7] offset:16 nt
	s_add_u32 s6, s6, 0x400000
	s_addc_u32 s7, s7, 0
	s_waitcnt vmcnt(21)
	v_cvt_pk_fp8_f32 v8, v120, v121
	v_cvt_pk_fp8_f32 v9, v122, v123
	v_cvt_pk_fp8_f32 v10, v124, v125
	v_cvt_pk_fp8_f32 v11, v126, v127
	v_and_b32_e32 v8, 0xffff, v8
	v_and_b32_e32 v10, 0xffff, v10
	v_lshl_or_b32 v142, v9, 16, v8
	v_lshl_or_b32 v143, v11, 16, v10
	global_store_dwordx2 v3, v[142:143], s[8:9] sc1
	s_add_u32 s8, s8, 0x100000
	s_addc_u32 s9, s9, 0
	global_load_dwordx4 v[120:123], v2, s[6:7] nt
	global_load_dwordx4 v[124:127], v2, s[6:7] offset:16 nt
	s_add_u32 s6, s6, 0x400000
	s_addc_u32 s7, s7, 0
	s_waitcnt vmcnt(21)
	v_cvt_pk_fp8_f32 v8, v64, v65
	v_cvt_pk_fp8_f32 v9, v66, v67
	v_cvt_pk_fp8_f32 v10, v68, v69
	v_cvt_pk_fp8_f32 v11, v70, v71
	v_and_b32_e32 v8, 0xffff, v8
	v_and_b32_e32 v10, 0xffff, v10
	v_lshl_or_b32 v128, v9, 16, v8
	v_lshl_or_b32 v129, v11, 16, v10
	global_store_dwordx2 v3, v[128:129], s[8:9] sc1
	s_add_u32 s8, s8, 0x100000
	s_addc_u32 s9, s9, 0
	global_load_dwordx4 v[64:67], v2, s[6:7] nt
	global_load_dwordx4 v[68:71], v2, s[6:7] offset:16 nt
	s_add_u32 s6, s6, 0x400000
	s_addc_u32 s7, s7, 0
	s_waitcnt vmcnt(21)
	v_cvt_pk_fp8_f32 v8, v72, v73
	v_cvt_pk_fp8_f32 v9, v74, v75
	v_cvt_pk_fp8_f32 v10, v76, v77
	v_cvt_pk_fp8_f32 v11, v78, v79
	v_and_b32_e32 v8, 0xffff, v8
	v_and_b32_e32 v10, 0xffff, v10
	v_lshl_or_b32 v130, v9, 16, v8
	v_lshl_or_b32 v131, v11, 16, v10
	global_store_dwordx2 v3, v[130:131], s[8:9] sc1
	s_add_u32 s8, s8, 0x100000
	s_addc_u32 s9, s9, 0
	global_load_dwordx4 v[72:75], v2, s[6:7] nt
	global_load_dwordx4 v[76:79], v2, s[6:7] offset:16 nt
	s_add_u32 s6, s6, 0x400000
	s_addc_u32 s7, s7, 0
	s_waitcnt vmcnt(21)
	v_cvt_pk_fp8_f32 v8, v80, v81
	v_cvt_pk_fp8_f32 v9, v82, v83
	v_cvt_pk_fp8_f32 v10, v84, v85
	v_cvt_pk_fp8_f32 v11, v86, v87
	v_and_b32_e32 v8, 0xffff, v8
	v_and_b32_e32 v10, 0xffff, v10
	v_lshl_or_b32 v132, v9, 16, v8
	v_lshl_or_b32 v133, v11, 16, v10
	global_store_dwordx2 v3, v[132:133], s[8:9] sc1
	s_add_u32 s8, s8, 0x100000
	s_addc_u32 s9, s9, 0
	global_load_dwordx4 v[80:83], v2, s[6:7] nt
	global_load_dwordx4 v[84:87], v2, s[6:7] offset:16 nt
	s_add_u32 s6, s6, 0x400000
	s_addc_u32 s7, s7, 0
	s_waitcnt vmcnt(21)
	v_cvt_pk_fp8_f32 v8, v88, v89
	v_cvt_pk_fp8_f32 v9, v90, v91
	v_cvt_pk_fp8_f32 v10, v92, v93
	v_cvt_pk_fp8_f32 v11, v94, v95
	v_and_b32_e32 v8, 0xffff, v8
	v_and_b32_e32 v10, 0xffff, v10
	v_lshl_or_b32 v134, v9, 16, v8
	v_lshl_or_b32 v135, v11, 16, v10
	global_store_dwordx2 v3, v[134:135], s[8:9] sc1
	s_add_u32 s8, s8, 0x100000
	s_addc_u32 s9, s9, 0
	global_load_dwordx4 v[88:91], v2, s[6:7] nt
	global_load_dwordx4 v[92:95], v2, s[6:7] offset:16 nt
	s_add_u32 s6, s6, 0x400000
	s_addc_u32 s7, s7, 0
	s_waitcnt vmcnt(21)
	v_cvt_pk_fp8_f32 v8, v96, v97
	v_cvt_pk_fp8_f32 v9, v98, v99
	v_cvt_pk_fp8_f32 v10, v100, v101
	v_cvt_pk_fp8_f32 v11, v102, v103
	v_and_b32_e32 v8, 0xffff, v8
	v_and_b32_e32 v10, 0xffff, v10
	v_lshl_or_b32 v136, v9, 16, v8
	v_lshl_or_b32 v137, v11, 16, v10
	global_store_dwordx2 v3, v[136:137], s[8:9] sc1
	s_add_u32 s8, s8, 0x100000
	s_addc_u32 s9, s9, 0
	global_load_dwordx4 v[96:99], v2, s[6:7] nt
	global_load_dwordx4 v[100:103], v2, s[6:7] offset:16 nt
	s_add_u32 s6, s6, 0x400000
	s_addc_u32 s7, s7, 0
	s_waitcnt vmcnt(21)
	v_cvt_pk_fp8_f32 v8, v104, v105
	v_cvt_pk_fp8_f32 v9, v106, v107
	v_cvt_pk_fp8_f32 v10, v108, v109
	v_cvt_pk_fp8_f32 v11, v110, v111
	v_and_b32_e32 v8, 0xffff, v8
	v_and_b32_e32 v10, 0xffff, v10
	v_lshl_or_b32 v138, v9, 16, v8
	v_lshl_or_b32 v139, v11, 16, v10
	global_store_dwordx2 v3, v[138:139], s[8:9] sc1
	s_add_u32 s8, s8, 0x100000
	s_addc_u32 s9, s9, 0
	global_load_dwordx4 v[104:107], v2, s[6:7] nt
	global_load_dwordx4 v[108:111], v2, s[6:7] offset:16 nt
	s_add_u32 s6, s6, 0x400000
	s_addc_u32 s7, s7, 0
	s_waitcnt vmcnt(21)
	v_cvt_pk_fp8_f32 v8, v112, v113
	v_cvt_pk_fp8_f32 v9, v114, v115
	v_cvt_pk_fp8_f32 v10, v116, v117
	v_cvt_pk_fp8_f32 v11, v118, v119
	v_and_b32_e32 v8, 0xffff, v8
	v_and_b32_e32 v10, 0xffff, v10
	v_lshl_or_b32 v140, v9, 16, v8
	v_lshl_or_b32 v141, v11, 16, v10
	global_store_dwordx2 v3, v[140:141], s[8:9] sc1
	s_add_u32 s8, s8, 0x100000
	s_addc_u32 s9, s9, 0
	global_load_dwordx4 v[112:115], v2, s[6:7] nt
	global_load_dwordx4 v[116:119], v2, s[6:7] offset:16 nt
	s_add_u32 s6, s6, 0x400000
	s_addc_u32 s7, s7, 0
	s_waitcnt vmcnt(21)
	v_cvt_pk_fp8_f32 v8, v120, v121
	v_cvt_pk_fp8_f32 v9, v122, v123
	v_cvt_pk_fp8_f32 v10, v124, v125
	v_cvt_pk_fp8_f32 v11, v126, v127
	v_and_b32_e32 v8, 0xffff, v8
	v_and_b32_e32 v10, 0xffff, v10
	v_lshl_or_b32 v142, v9, 16, v8
	v_lshl_or_b32 v143, v11, 16, v10
	global_store_dwordx2 v3, v[142:143], s[8:9] sc1
	s_add_u32 s8, s8, 0x100000
	s_addc_u32 s9, s9, 0
	global_load_dwordx4 v[120:123], v2, s[6:7] nt
	global_load_dwordx4 v[124:127], v2, s[6:7] offset:16 nt
	s_add_u32 s6, s6, 0x400000
	s_addc_u32 s7, s7, 0
	s_waitcnt vmcnt(21)
	v_cvt_pk_fp8_f32 v8, v64, v65
	v_cvt_pk_fp8_f32 v9, v66, v67
	v_cvt_pk_fp8_f32 v10, v68, v69
	v_cvt_pk_fp8_f32 v11, v70, v71
	v_and_b32_e32 v8, 0xffff, v8
	v_and_b32_e32 v10, 0xffff, v10
	v_lshl_or_b32 v128, v9, 16, v8
	v_lshl_or_b32 v129, v11, 16, v10
	global_store_dwordx2 v3, v[128:129], s[8:9] sc1
	s_add_u32 s8, s8, 0x100000
	s_addc_u32 s9, s9, 0
	global_load_dwordx4 v[64:67], v2, s[6:7] nt
	global_load_dwordx4 v[68:71], v2, s[6:7] offset:16 nt
	s_add_u32 s6, s6, 0x400000
	s_addc_u32 s7, s7, 0
	s_waitcnt vmcnt(21)
; __device__ __forceinline__ unsigned cvt_pk_bf16(float lo, float hi) { unsigned r; asm volatile("v_cvt_pk_bf16_f32 %0, %1, %2" : "=v"(r) : "v"(lo), "v"(hi)); return r; }
; __global__ void __launch_bounds__(512, 2) hybrid_fwd(Args a) {
;     ...
;             for (size_t i0 = gt; i0 < NCH; i0 += 4 * GT) {
;                 f32x4 v[4][2];
; #pragma unroll
;                 for (int u = 0; u < 4; ++u) { const size_t i = i0 + (size_t)u * GT; if (i < NCH) { v[u][0] = ((const f32x4*)a.x)[2 * i]; v[u][1] = ((const f32x4*)a.x)[2 * i + 1]; } }
; #pragma unroll
;                 for (int u = 0; u < 4; ++u) { const size_t i = i0 + (size_t)u * GT; if (i < NCH) {
;                     u32x4 w; w.x = cvt_pk_bf16(v[u][0][0], v[u][0][1]); w.y = cvt_pk_bf16(v[u][0][2], v[u][0][3]); w.z = cvt_pk_bf16(v[u][1][0], v[u][1][1]); w.w = cvt_pk_bf16(v[u][1][2], v[u][1][3]);
;                     if (a.n_bf16 > 0) ((u32x4*)XB)[i] = w;
;                     const unsigned p0 = pack_fp8x4(v[u][0][0], v[u][0][1], v[u][0][2], v[u][0][3]), p1 = pack_fp8x4(v[u][1][0], v[u][1][1], v[u][1][2], v[u][1][3]);
;                     ((u32x2*)XB8)[i] = (u32x2){p0, p1}; } }
	v_cvt_pk_fp8_f32 v8, v72, v73
	v_cvt_pk_fp8_f32 v9, v74, v75
	v_cvt_pk_fp8_f32 v10, v76, v77
	v_cvt_pk_fp8_f32 v11, v78, v79
	v_and_b32_e32 v8, 0xffff, v8
	v_and_b32_e32 v10, 0xffff, v10
	v_lshl_or_b32 v130, v9, 16, v8
	v_lshl_or_b32 v131, v11, 16, v10
	global_store_dwordx2 v3, v[130:131], s[8:9] sc1
	s_add_u32 s8, s8, 0x100000
	s_addc_u32 s9, s9, 0
	global_load_dwordx4 v[72:75], v2, s[6:7] nt
	global_load_dwordx4 v[76:79], v2, s[6:7] offset:16 nt
	s_add_u32 s6, s6, 0x400000
	s_addc_u32 s7, s7, 0
	s_waitcnt vmcnt(21)
	v_cvt_pk_fp8_f32 v8, v80, v81
	v_cvt_pk_fp8_f32 v9, v82, v83
	v_cvt_pk_fp8_f32 v10, v84, v85
	v_cvt_pk_fp8_f32 v11, v86, v87
	v_and_b32_e32 v8, 0xffff, v8
	v_and_b32_e32 v10, 0xffff, v10
	v_lshl_or_b32 v132, v9, 16, v8
	v_lshl_or_b32 v133, v11, 16, v10
	global_store_dwordx2 v3, v[132:133], s[8:9] sc1
	s_add_u32 s8, s8, 0x100000
	s_addc_u32 s9, s9, 0
	global_load_dwordx4 v[80:83], v2, s[6:7] nt
	global_load_dwordx4 v[84:87], v2, s[6:7] offset:16 nt
	s_add_u32 s6, s6, 0x400000
	s_addc_u32 s7, s7, 0
	s_waitcnt vmcnt(21)
	v_cvt_pk_fp8_f32 v8, v88, v89
	v_cvt_pk_fp8_f32 v9, v90, v91
	v_cvt_pk_fp8_f32 v10, v92, v93
	v_cvt_pk_fp8_f32 v11, v94, v95
	v_and_b32_e32 v8, 0xffff, v8
	v_and_b32_e32 v10, 0xffff, v10
	v_lshl_or_b32 v134, v9, 16, v8
	v_lshl_or_b32 v135, v11, 16, v10
	global_store_dwordx2 v3, v[134:135], s[8:9] sc1
	s_add_u32 s8, s8, 0x100000
	s_addc_u32 s9, s9, 0
	global_load_dwordx4 v[88:91], v2, s[6:7] nt
	global_load_dwordx4 v[92:95], v2, s[6:7] offset:16 nt
	s_add_u32 s6, s6, 0x400000
	s_addc_u32 s7, s7, 0
	s_waitcnt vmcnt(21)
	v_cvt_pk_fp8_f32 v8, v96, v97
	v_cvt_pk_fp8_f32 v9, v98, v99
	v_cvt_pk_fp8_f32 v10, v100, v101
	v_cvt_pk_fp8_f32 v11, v102, v103
	v_and_b32_e32 v8, 0xffff, v8
	v_and_b32_e32 v10, 0xffff, v10
	v_lshl_or_b32 v136, v9, 16, v8
	v_lshl_or_b32 v137, v11, 16, v10
	global_store_dwordx2 v3, v[136:137], s[8:9] sc1
	s_add_u32 s8, s8, 0x100000
	s_addc_u32 s9, s9, 0
	global_load_dwordx4 v[96:99], v2, s[6:7] nt
	global_load_dwordx4 v[100:103], v2, s[6:7] offset:16 nt
	s_add_u32 s6, s6, 0x400000
	s_addc_u32 s7, s7, 0
	s_waitcnt vmcnt(21)
	v_cvt_pk_fp8_f32 v8, v104, v105
	v_cvt_pk_fp8_f32 v9, v106, v107
	v_cvt_pk_fp8_f32 v10, v108, v109
	v_cvt_pk_fp8_f32 v11, v110, v111
	v_and_b32_e32 v8, 0xffff, v8
	v_and_b32_e32 v10, 0xffff, v10
	v_lshl_or_b32 v138, v9, 16, v8
	v_lshl_or_b32 v139, v11, 16, v10
	global_store_dwordx2 v3, v[138:139], s[8:9] sc1
	s_add_u32 s8, s8, 0x100000
	s_addc_u32 s9, s9, 0
	global_load_dwordx4 v[104:107], v2, s[6:7] nt
	global_load_dwordx4 v[108:111], v2, s[6:7] offset:16 nt
	s_add_u32 s6, s6, 0x400000
	s_addc_u32 s7, s7, 0
	s_waitcnt vmcnt(21)
	v_cvt_pk_fp8_f32 v8, v112, v113
	v_cvt_pk_fp8_f32 v9, v114, v115
	v_cvt_pk_fp8_f32 v10, v116, v117
	v_cvt_pk_fp8_f32 v11, v118, v119
	v_and_b32_e32 v8, 0xffff, v8
	v_and_b32_e32 v10, 0xffff, v10
	v_lshl_or_b32 v140, v9, 16, v8
	v_lshl_or_b32 v141, v11, 16, v10
	global_store_dwordx2 v3, v[140:141], s[8:9] sc1
	s_add_u32 s8, s8, 0x100000
	s_addc_u32 s9, s9, 0
	global_load_dwordx4 v[112:115], v2, s[6:7] nt
	global_load_dwordx4 v[116:119], v2, s[6:7] offset:16 nt
	s_add_u32 s6, s6, 0x400000
	s_addc_u32 s7, s7, 0
	s_waitcnt vmcnt(21)
	v_cvt_pk_fp8_f32 v8, v120, v121
	v_cvt_pk_fp8_f32 v9, v122, v123
	v_cvt_pk_fp8_f32 v10, v124, v125
	v_cvt_pk_fp8_f32 v11, v126, v127
	v_and_b32_e32 v8, 0xffff, v8
	v_and_b32_e32 v10, 0xffff, v10
	v_lshl_or_b32 v142, v9, 16, v8
	v_lshl_or_b32 v143, v11, 16, v10
	global_store_dwordx2 v3, v[142:143], s[8:9] sc1
	s_add_u32 s8, s8, 0x100000
	s_addc_u32 s9, s9, 0
	global_load_dwordx4 v[120:123], v2, s[6:7] nt
	global_load_dwordx4 v[124:127], v2, s[6:7] offset:16 nt
	s_add_u32 s6, s6, 0x400000
	s_addc_u32 s7, s7, 0
	s_waitcnt vmcnt(21)
	v_cvt_pk_fp8_f32 v8, v64, v65
	v_cvt_pk_fp8_f32 v9, v66, v67
	v_cvt_pk_fp8_f32 v10, v68, v69
	v_cvt_pk_fp8_f32 v11, v70, v71
	v_and_b32_e32 v8, 0xffff, v8
	v_and_b32_e32 v10, 0xffff, v10
	v_lshl_or_b32 v128, v9, 16, v8
	v_lshl_or_b32 v129, v11, 16, v10
	global_store_dwordx2 v3, v[128:129], s[8:9] sc1
	s_add_u32 s8, s8, 0x100000
	s_addc_u32 s9, s9, 0
	s_waitcnt vmcnt(19)
	v_cvt_pk_fp8_f32 v8, v72, v73
	v_cvt_pk_fp8_f32 v9, v74, v75
	v_cvt_pk_fp8_f32 v10, v76, v77
	v_cvt_pk_fp8_f32 v11, v78, v79
	v_and_b32_e32 v8, 0xffff, v8
	v_and_b32_e32 v10, 0xffff, v10
	v_lshl_or_b32 v130, v9, 16, v8
	v_lshl_or_b32 v131, v11, 16, v10
	global_store_dwordx2 v3, v[130:131], s[8:9] sc1
	s_add_u32 s8, s8, 0x100000
	s_addc_u32 s9, s9, 0
	s_waitcnt vmcnt(17)
	v_cvt_pk_fp8_f32 v8, v80, v81
	v_cvt_pk_fp8_f32 v9, v82, v83
	v_cvt_pk_fp8_f32 v10, v84, v85
	v_cvt_pk_fp8_f32 v11, v86, v87
	v_and_b32_e32 v8, 0xffff, v8
	v_and_b32_e32 v10, 0xffff, v10
	v_lshl_or_b32 v132, v9, 16, v8
	v_lshl_or_b32 v133, v11, 16, v10
	global_store_dwordx2 v3, v[132:133], s[8:9] sc1
	s_add_u32 s8, s8, 0x100000
	s_addc_u32 s9, s9, 0
	s_waitcnt vmcnt(15)
	v_cvt_pk_fp8_f32 v8, v88, v89
	v_cvt_pk_fp8_f32 v9, v90, v91
	v_cvt_pk_fp8_f32 v10, v92, v93
	v_cvt_pk_fp8_f32 v11, v94, v95
	v_and_b32_e32 v8, 0xffff, v8
	v_and_b32_e32 v10, 0xffff, v10
	v_lshl_or_b32 v134, v9, 16, v8
	v_lshl_or_b32 v135, v11, 16, v10
	global_store_dwordx2 v3, v[134:135], s[8:9] sc1
	s_add_u32 s8, s8, 0x100000
	s_addc_u32 s9, s9, 0
	s_waitcnt vmcnt(13)
	v_cvt_pk_fp8_f32 v8, v96, v97
	v_cvt_pk_fp8_f32 v9, v98, v99
	v_cvt_pk_fp8_f32 v10, v100, v101
	v_cvt_pk_fp8_f32 v11, v102, v103
	v_and_b32_e32 v8, 0xffff, v8
	v_and_b32_e32 v10, 0xffff, v10
	v_lshl_or_b32 v136, v9, 16, v8
	v_lshl_or_b32 v137, v11, 16, v10
	global_store_dwordx2 v3, v[136:137], s[8:9] sc1
	s_add_u32 s8, s8, 0x100000
	s_addc_u32 s9, s9, 0
	s_waitcnt vmcnt(11)
; __device__ __forceinline__ unsigned cvt_pk_bf16(float lo, float hi) { unsigned r; asm volatile("v_cvt_pk_bf16_f32 %0, %1, %2" : "=v"(r) : "v"(lo), "v"(hi)); return r; }
; __global__ void __launch_bounds__(512, 2) hybrid_fwd(Args a) {
;     ...
;                 for (int u = 0; u < 4; ++u) { const size_t i = i0 + (size_t)u * GT; if (i < NCH) {
;                     u32x4 w; w.x = cvt_pk_bf16(v[u][0][0], v[u][0][1]); w.y = cvt_pk_bf16(v[u][0][2], v[u][0][3]); w.z = cvt_pk_bf16(v[u][1][0], v[u][1][1]); w.w = cvt_pk_bf16(v[u][1][2], v[u][1][3]);
;                     if (a.n_bf16 > 0) ((u32x4*)XB)[i] = w;
;                     const unsigned p0 = pack_fp8x4(v[u][0][0], v[u][0][1], v[u][0][2], v[u][0][3]), p1 = pack_fp8x4(v[u][1][0], v[u][1][1], v[u][1][2], v[u][1][3]);
;                     ((u32x2*)XB8)[i] = (u32x2){p0, p1}; } }
;     ...
;         for (size_t i = gt; i < (size_t)M * 64; i += GT) {
;             const int t = (int)(i >> 6), j = (int)(i & 63);
;             const float ang = (float)a.pos[t] * a.inv_freq[j];
;             const double rev = (double)ang * 0.15915494309189535; const float fr = (float)(rev - __builtin_rint(rev));
;             const f32x2 cs = (f32x2){__builtin_amdgcn_cosf(fr), __builtin_amdgcn_sinf(fr)};
;             csB[i] = cs; if ((j & 1) == 0) csA[(size_t)t * 32 + (j >> 1)] = cs;
;         }
	v_cvt_pk_fp8_f32 v8, v104, v105
	v_cvt_pk_fp8_f32 v9, v106, v107
	v_cvt_pk_fp8_f32 v10, v108, v109
	v_cvt_pk_fp8_f32 v11, v110, v111
	v_and_b32_e32 v8, 0xffff, v8
	v_and_b32_e32 v10, 0xffff, v10
	v_lshl_or_b32 v138, v9, 16, v8
	v_lshl_or_b32 v139, v11, 16, v10
	global_store_dwordx2 v3, v[138:139], s[8:9] sc1
	s_add_u32 s8, s8, 0x100000
	s_addc_u32 s9, s9, 0
	s_waitcnt vmcnt(9)
	v_cvt_pk_fp8_f32 v8, v112, v113
	v_cvt_pk_fp8_f32 v9, v114, v115
	v_cvt_pk_fp8_f32 v10, v116, v117
	v_cvt_pk_fp8_f32 v11, v118, v119
	v_and_b32_e32 v8, 0xffff, v8
	v_and_b32_e32 v10, 0xffff, v10
	v_lshl_or_b32 v140, v9, 16, v8
	v_lshl_or_b32 v141, v11, 16, v10
	global_store_dwordx2 v3, v[140:141], s[8:9] sc1
	s_add_u32 s8, s8, 0x100000
	s_addc_u32 s9, s9, 0
	s_waitcnt vmcnt(7)
	v_cvt_pk_fp8_f32 v8, v120, v121
	v_cvt_pk_fp8_f32 v9, v122, v123
	v_cvt_pk_fp8_f32 v10, v124, v125
	v_cvt_pk_fp8_f32 v11, v126, v127
	v_and_b32_e32 v8, 0xffff, v8
	v_and_b32_e32 v10, 0xffff, v10
	v_lshl_or_b32 v142, v9, 16, v8
	v_lshl_or_b32 v143, v11, 16, v10
	global_store_dwordx2 v3, v[142:143], s[8:9] sc1
	s_add_u32 s8, s8, 0x100000
	s_addc_u32 s9, s9, 0
	s_lshr_b32 s10, s33, 6
	s_lshl_b32 s11, s2, 3
	s_add_u32 s10, s10, s11
	s_lshl_b32 s11, s10, 2
	s_add_u32 s24, s20, s11
	s_addc_u32 s25, s21, 0
	s_load_dword s34, s[24:25], 0x0
	s_load_dword s35, s[24:25], 0x2000
	s_load_dword s36, s[24:25], 0x4000
	s_load_dword s37, s[24:25], 0x6000
	s_load_dword s38, s[24:25], 0x8000
	s_load_dword s39, s[24:25], 0xa000
	s_load_dword s40, s[24:25], 0xc000
	s_load_dword s41, s[24:25], 0xe000
	v_lshlrev_b32_e32 v5, 2, v4
	global_load_dword v5, v5, s[70:71] offset:96
	v_lshlrev_b32_e32 v6, 3, v4
	v_lshrrev_b32_e32 v7, 1, v4
	v_lshlrev_b32_e32 v7, 3, v7
	s_lshl_b32 s11, s10, 9
	s_add_u32 s26, s90, s11
	s_addc_u32 s27, s91, 0
	s_add_u32 s26, s26, 0x7c00000
	s_addc_u32 s27, s27, 0
	s_lshl_b32 s11, s10, 8
	s_add_u32 s28, s90, s11
	s_addc_u32 s29, s91, 0
	s_add_u32 s28, s28, 0x8400000
	s_addc_u32 s29, s29, 0
	s_mov_b32 s42, 0x6dc9c883
	s_mov_b32 s43, 0x3fc45f30
	s_waitcnt vmcnt(0) lgkmcnt(0)
	v_cvt_f32_i32_e32 v16, s34
	v_mul_f32_e32 v16, v5, v16
	v_cvt_f64_f32_e32 v[16:17], v16
	v_mul_f64 v[12:13], v[16:17], s[42:43]
	v_rndne_f64_e32 v[12:13], v[12:13]
	v_fma_f64 v[16:17], v[16:17], s[42:43], -v[12:13]
	v_cvt_f32_f64_e32 v17, v[16:17]
	v_cos_f32_e32 v16, v17
	v_sin_f32_e32 v17, v17
	v_cvt_f32_i32_e32 v18, s35
	v_mul_f32_e32 v18, v5, v18
	v_cvt_f64_f32_e32 v[18:19], v18
	v_mul_f64 v[12:13], v[18:19], s[42:43]
	v_rndne_f64_e32 v[12:13], v[12:13]
	v_fma_f64 v[18:19], v[18:19], s[42:43], -v[12:13]
	v_cvt_f32_f64_e32 v19, v[18:19]
	v_cos_f32_e32 v18, v19
	v_sin_f32_e32 v19, v19
	v_cvt_f32_i32_e32 v20, s36
	v_mul_f32_e32 v20, v5, v20
	v_cvt_f64_f32_e32 v[20:21], v20
	v_mul_f64 v[12:13], v[20:21], s[42:43]
	v_rndne_f64_e32 v[12:13], v[12:13]
	v_fma_f64 v[20:21], v[20:21], s[42:43], -v[12:13]
	v_cvt_f32_f64_e32 v21, v[20:21]
	v_cos_f32_e32 v20, v21
	v_sin_f32_e32 v21, v21
	v_cvt_f32_i32_e32 v22, s37
	v_mul_f32_e32 v22, v5, v22
	v_cvt_f64_f32_e32 v[22:23], v22
	v_mul_f64 v[12:13], v[22:23], s[42:43]
	v_rndne_f64_e32 v[12:13], v[12:13]
	v_fma_f64 v[22:23], v[22:23], s[42:43], -v[12:13]
	v_cvt_f32_f64_e32 v23, v[22:23]
	v_cos_f32_e32 v22, v23
	v_sin_f32_e32 v23, v23
	v_cvt_f32_i32_e32 v24, s38
	v_mul_f32_e32 v24, v5, v24
	v_cvt_f64_f32_e32 v[24:25], v24
	v_mul_f64 v[12:13], v[24:25], s[42:43]
	v_rndne_f64_e32 v[12:13], v[12:13]
	v_fma_f64 v[24:25], v[24:25], s[42:43], -v[12:13]
	v_cvt_f32_f64_e32 v25, v[24:25]
	v_cos_f32_e32 v24, v25
	v_sin_f32_e32 v25, v25
	v_cvt_f32_i32_e32 v26, s39
	v_mul_f32_e32 v26, v5, v26
	v_cvt_f64_f32_e32 v[26:27], v26
	v_mul_f64 v[12:13], v[26:27], s[42:43]
	v_rndne_f64_e32 v[12:13], v[12:13]
	v_fma_f64 v[26:27], v[26:27], s[42:43], -v[12:13]
	v_cvt_f32_f64_e32 v27, v[26:27]
	v_cos_f32_e32 v26, v27
	v_sin_f32_e32 v27, v27
	v_cvt_f32_i32_e32 v28, s40
	v_mul_f32_e32 v28, v5, v28
	v_cvt_f64_f32_e32 v[28:29], v28
	v_mul_f64 v[12:13], v[28:29], s[42:43]
	v_rndne_f64_e32 v[12:13], v[12:13]
	v_fma_f64 v[28:29], v[28:29], s[42:43], -v[12:13]
	v_cvt_f32_f64_e32 v29, v[28:29]
	v_cos_f32_e32 v28, v29
	v_sin_f32_e32 v29, v29
	v_cvt_f32_i32_e32 v30, s41
	v_mul_f32_e32 v30, v5, v30
	v_cvt_f64_f32_e32 v[30:31], v30
	v_mul_f64 v[12:13], v[30:31], s[42:43]
	v_rndne_f64_e32 v[12:13], v[12:13]
	v_fma_f64 v[30:31], v[30:31], s[42:43], -v[12:13]
	v_cvt_f32_f64_e32 v31, v[30:31]
	v_cos_f32_e32 v30, v31
	v_sin_f32_e32 v31, v31
	s_nop 1
	global_store_dwordx2 v6, v[16:17], s[26:27] sc1
	s_add_u32 s26, s26, 0x100000
	s_addc_u32 s27, s27, 0
	global_store_dwordx2 v6, v[18:19], s[26:27] sc1
	s_add_u32 s26, s26, 0x100000
	s_addc_u32 s27, s27, 0
	global_store_dwordx2 v6, v[20:21], s[26:27] sc1
	s_add_u32 s26, s26, 0x100000
	s_addc_u32 s27, s27, 0
	global_store_dwordx2 v6, v[22:23], s[26:27] sc1
	s_add_u32 s26, s26, 0x100000
	s_addc_u32 s27, s27, 0
	global_store_dwordx2 v6, v[24:25], s[26:27] sc1
	s_add_u32 s26, s26, 0x100000
	s_addc_u32 s27, s27, 0
	global_store_dwordx2 v6, v[26:27], s[26:27] sc1
	s_add_u32 s26, s26, 0x100000
	s_addc_u32 s27, s27, 0
	global_store_dwordx2 v6, v[28:29], s[26:27] sc1
	s_add_u32 s26, s26, 0x100000
	s_addc_u32 s27, s27, 0
	global_store_dwordx2 v6, v[30:31], s[26:27] sc1
	s_mov_b32 exec_lo, 0x55555555
	s_mov_b32 exec_hi, 0x55555555
	s_nop 1
	global_store_dwordx2 v7, v[16:17], s[28:29] sc1
	s_add_u32 s28, s28, 0x80000
	s_addc_u32 s29, s29, 0
	global_store_dwordx2 v7, v[18:19], s[28:29] sc1
	s_add_u32 s28, s28, 0x80000
	s_addc_u32 s29, s29, 0
	global_store_dwordx2 v7, v[20:21], s[28:29] sc1
	s_add_u32 s28, s28, 0x80000
	s_addc_u32 s29, s29, 0
	global_store_dwordx2 v7, v[22:23], s[28:29] sc1
	s_add_u32 s28, s28, 0x80000
	s_addc_u32 s29, s29, 0
	global_store_dwordx2 v7, v[24:25], s[28:29] sc1
	s_add_u32 s28, s28, 0x80000
	s_addc_u32 s29, s29, 0
	global_store_dwordx2 v7, v[26:27], s[28:29] sc1
	s_add_u32 s28, s28, 0x80000
	s_addc_u32 s29, s29, 0
	global_store_dwordx2 v7, v[28:29], s[28:29] sc1
	s_add_u32 s28, s28, 0x80000
	s_addc_u32 s29, s29, 0
	global_store_dwordx2 v7, v[30:31], s[28:29] sc1
	s_mov_b64 exec, -1
	s_nop 1
	v_and_b32_e32 v12, 7, v4
	v_lshrrev_b32_e32 v13, 3, v4
	v_lshlrev_b32_e32 v14, 4, v12
	s_mov_b32 s10, 0x5a000
	v_mul_lo_u32 v15, v13, s10
	v_add_u32_e32 v162, v15, v14
	v_add_u32_e32 v163, 0xb400, v162
	v_add_u32_e32 v164, 0x16800, v162
	v_add_u32_e32 v165, 0x21c00, v162
	v_add_u32_e32 v166, 0x2d000, v162
	v_add_u32_e32 v167, 0x38400, v162
	v_add_u32_e32 v168, 0x43800, v162
	v_add_u32_e32 v169, 0x4ec00, v162
	v_lshlrev_b32_e32 v14, 14, v12
	v_lshl_add_u32 v170, v13, 3, v14
	v_add_u32_e32 v171, 0x1000, v170
	v_add_u32_e32 v172, 0x2000, v170
	v_add_u32_e32 v173, 0x3000, v170
	s_mov_b32 s44, 0x42800000
	s_mov_b32 s45, 0x42800000
	s_lshr_b32 s10, s33, 6
	s_lshl_b32 s11, s2, 3
	s_add_u32 s46, s10, s11
	s_add_u32 s64, s90, 0x4000000
	s_addc_u32 s65, s91, 0
	s_cmpk_ge_u32 s46, 0x680
	s_cbranch_scc1 .Lp0c_four
; #define LAS __attribute__((address_space(3)))
; __device__ __forceinline__ void transpose_item_fp8(const float* W, int N, unsigned char* W8, int pitch, int kofs, int k0, int n_src, int n_dst, float scale, LAS float* scr, int lane) {
;     const int r8 = lane >> 3, c4 = lane & 7;
;     f32x4 v[8];
; #pragma unroll
;     for (int i = 0; i < 8; ++i) v[i] = *(const f32x4*)(W + (size_t)(k0 + r8 + 8 * i) * N + n_src + 4 * c4);
; #pragma unroll
;     for (int i = 0; i < 8; ++i) { LAS float* d = scr + (r8 + 8 * i) * 33 + 4 * c4; d[0] = v[i][0]; d[1] = v[i][1]; d[2] = v[i][2]; d[3] = v[i][3]; }
;     asm volatile("s_waitcnt lgkmcnt(0)" ::: "memory");
;     const int n = lane & 31, cp = lane >> 5;
; #pragma unroll
;     for (int q = 0; q < 2; ++q) { const int ck = (2 * cp + q) * 16; const LAS float* sp = scr + ck * 33 + n; u32x4 o;
; #pragma unroll
;         for (int w = 0; w < 4; ++w) o[w] = pack_fp8x4(sp[(4 * w) * 33] * scale, sp[(4 * w + 1) * 33] * scale, sp[(4 * w + 2) * 33] * scale, sp[(4 * w + 3) * 33] * scale);
;         *(u32x4*)(W8 + (size_t)(n_dst + n) * pitch + kofs + k0 + ck) = o; }
; __global__ void __launch_bounds__(512, 2) hybrid_fwd(Args a) {
;     ...
;         constexpr int I_IN = (D / 64) * (DIN / 32);
;         for (int it = gw; it < I_IN; it += NGW) { const int nb = it % (DIN / 32), kb = it / (DIN / 32);
;             if ((a.fp8mask >> (nb >> 3)) & 1ull) transpose_item_fp8(a.w_in, DIN, (unsigned char*)WinT, 4096, 0, 64 * kb, gemm_col_to_orig(32 * nb), 32 * nb, W8_SCALE, scr, lane);
	s_add_u32 s47, s46, 0x0
	s_mul_hi_u32 s48, s47, 0xb60b61
	s_mul_i32 s49, s48, 0x168
	s_sub_u32 s49, s47, s49
	s_lshl_b32 s50, s48, 1
	s_lshr_b32 s51, s49, 3
	s_and_b32 s52, s49, 7
	s_and_b32 s53, s52, 3
	s_lshr_b32 s54, s52, 2
	s_lshl_b32 s55, s53, 6
	s_lshl_b32 s56, s54, 5
	s_add_u32 s55, s55, s56
	s_bfe_u32 s56, s52, 0x10001
	s_lshl_b32 s56, s56, 7
	s_and_b32 s57, s52, 1
	s_lshl_b32 s57, s57, 5
	s_add_u32 s56, s56, s57
	s_lshl_b32 s57, s54, 6
	s_add_u32 s56, s56, s57
	s_lshl_b32 s57, s52, 5
	s_sub_u32 s58, s51, 9
	s_cmp_lt_u32 s58, 12
	s_cselect_b32 s57, s56, s57
	s_cmp_lt_u32 s51, 5
	s_cselect_b32 s57, s55, s57
	s_lshl_b32 s58, s51, 8
	s_add_u32 s57, s57, s58
	s_mul_i32 s58, s50, 0x2d0000
	s_lshl_b32 s57, s57, 2
	s_add_u32 s58, s58, s57
	s_add_u32 s60, s22, s58
	s_addc_u32 s61, s23, 0
	s_lshl_b32 s58, s49, 17
	s_lshl_b32 s59, s50, 6
	s_add_u32 s58, s58, s59
	s_add_u32 s74, s64, s58
	s_addc_u32 s75, s65, 0
	global_load_dwordx4 v[64:67], v162, s[60:61] nt
	global_load_dwordx4 v[68:71], v163, s[60:61] nt
	global_load_dwordx4 v[72:75], v164, s[60:61] nt
	global_load_dwordx4 v[76:79], v165, s[60:61] nt
	global_load_dwordx4 v[80:83], v166, s[60:61] nt
	global_load_dwordx4 v[84:87], v167, s[60:61] nt
	global_load_dwordx4 v[88:91], v168, s[60:61] nt
	global_load_dwordx4 v[92:95], v169, s[60:61] nt
	s_add_u32 s47, s46, 0x0
	s_mul_hi_u32 s48, s47, 0xb60b61
	s_mul_i32 s49, s48, 0x168
	s_sub_u32 s49, s47, s49
	s_lshl_b32 s50, s48, 1
	s_or_b32 s50, s50, 1
	s_lshr_b32 s51, s49, 3
	s_and_b32 s52, s49, 7
	s_and_b32 s53, s52, 3
	s_lshr_b32 s54, s52, 2
	s_lshl_b32 s55, s53, 6
	s_lshl_b32 s56, s54, 5
	s_add_u32 s55, s55, s56
	s_bfe_u32 s56, s52, 0x10001
	s_lshl_b32 s56, s56, 7
	s_and_b32 s57, s52, 1
	s_lshl_b32 s57, s57, 5
	s_add_u32 s56, s56, s57
	s_lshl_b32 s57, s54, 6
	s_add_u32 s56, s56, s57
	s_lshl_b32 s57, s52, 5
	s_sub_u32 s58, s51, 9
	s_cmp_lt_u32 s58, 12
	s_cselect_b32 s57, s56, s57
	s_cmp_lt_u32 s51, 5
	s_cselect_b32 s57, s55, s57
	s_lshl_b32 s58, s51, 8
	s_add_u32 s57, s57, s58
	s_mul_i32 s58, s50, 0x2d0000
	s_lshl_b32 s57, s57, 2
	s_add_u32 s58, s58, s57
	s_add_u32 s60, s22, s58
	s_addc_u32 s61, s23, 0
	s_lshl_b32 s58, s49, 17
	s_lshl_b32 s59, s50, 6
	s_add_u32 s58, s58, s59
	s_add_u32 s76, s64, s58
	s_addc_u32 s77, s65, 0
	global_load_dwordx4 v[96:99], v162, s[60:61] nt
	global_load_dwordx4 v[100:103], v163, s[60:61] nt
	global_load_dwordx4 v[104:107], v164, s[60:61] nt
	global_load_dwordx4 v[108:111], v165, s[60:61] nt
	global_load_dwordx4 v[112:115], v166, s[60:61] nt
	global_load_dwordx4 v[116:119], v167, s[60:61] nt
	global_load_dwordx4 v[120:123], v168, s[60:61] nt
	global_load_dwordx4 v[124:127], v169, s[60:61] nt
	s_add_u32 s47, s46, 0x800
	s_mul_hi_u32 s48, s47, 0xb60b61
	s_mul_i32 s49, s48, 0x168
	s_sub_u32 s49, s47, s49
	s_lshl_b32 s50, s48, 1
	s_lshr_b32 s51, s49, 3
	s_and_b32 s52, s49, 7
	s_and_b32 s53, s52, 3
	s_lshr_b32 s54, s52, 2
	s_lshl_b32 s55, s53, 6
	s_lshl_b32 s56, s54, 5
	s_add_u32 s55, s55, s56
	s_bfe_u32 s56, s52, 0x10001
	s_lshl_b32 s56, s56, 7
	s_and_b32 s57, s52, 1
	s_lshl_b32 s57, s57, 5
	s_add_u32 s56, s56, s57
	s_lshl_b32 s57, s54, 6
	s_add_u32 s56, s56, s57
	s_lshl_b32 s57, s52, 5
	s_sub_u32 s58, s51, 9
	s_cmp_lt_u32 s58, 12
	s_cselect_b32 s57, s56, s57
	s_cmp_lt_u32 s51, 5
	s_cselect_b32 s57, s55, s57
	s_lshl_b32 s58, s51, 8
	s_add_u32 s57, s57, s58
	s_mul_i32 s58, s50, 0x2d0000
	s_lshl_b32 s57, s57, 2
	s_add_u32 s58, s58, s57
	s_add_u32 s60, s22, s58
	s_addc_u32 s61, s23, 0
	s_lshl_b32 s58, s49, 17
	s_lshl_b32 s59, s50, 6
	s_add_u32 s58, s58, s59
	s_add_u32 s78, s64, s58
	s_addc_u32 s79, s65, 0
	global_load_dwordx4 v[128:131], v162, s[60:61] nt
	global_load_dwordx4 v[132:135], v163, s[60:61] nt
	global_load_dwordx4 v[136:139], v164, s[60:61] nt
	global_load_dwordx4 v[140:143], v165, s[60:61] nt
	global_load_dwordx4 v[144:147], v166, s[60:61] nt
	global_load_dwordx4 v[148:151], v167, s[60:61] nt
	global_load_dwordx4 v[152:155], v168, s[60:61] nt
	global_load_dwordx4 v[156:159], v169, s[60:61] nt
	s_waitcnt vmcnt(16)
	v_pk_mul_f32 v[64:65], v[64:65], s[44:45]
	v_pk_mul_f32 v[66:67], v[66:67], s[44:45]
	v_pk_mul_f32 v[68:69], v[68:69], s[44:45]
	v_pk_mul_f32 v[70:71], v[70:71], s[44:45]
	v_pk_mul_f32 v[72:73], v[72:73], s[44:45]
	v_pk_mul_f32 v[74:75], v[74:75], s[44:45]
	v_pk_mul_f32 v[76:77], v[76:77], s[44:45]
	v_pk_mul_f32 v[78:79], v[78:79], s[44:45]
	v_pk_mul_f32 v[80:81], v[80:81], s[44:45]
	v_pk_mul_f32 v[82:83], v[82:83], s[44:45]
	v_pk_mul_f32 v[84:85], v[84:85], s[44:45]
	v_pk_mul_f32 v[86:87], v[86:87], s[44:45]
	v_pk_mul_f32 v[88:89], v[88:89], s[44:45]
	v_pk_mul_f32 v[90:91], v[90:91], s[44:45]
	v_pk_mul_f32 v[92:93], v[92:93], s[44:45]
	v_pk_mul_f32 v[94:95], v[94:95], s[44:45]
	v_cvt_pk_fp8_f32 v8, v64, v68
	v_cvt_pk_fp8_f32 v9, v72, v76
	v_cvt_pk_fp8_f32 v10, v80, v84
	v_cvt_pk_fp8_f32 v11, v88, v92
	v_and_b32_e32 v8, 0xffff, v8
	v_and_b32_e32 v10, 0xffff, v10
	v_lshl_or_b32 v176, v9, 16, v8
	v_lshl_or_b32 v177, v11, 16, v10
	global_store_dwordx2 v170, v[176:177], s[74:75] sc1
	v_cvt_pk_fp8_f32 v8, v65, v69
	v_cvt_pk_fp8_f32 v9, v73, v77
	v_cvt_pk_fp8_f32 v10, v81, v85
	v_cvt_pk_fp8_f32 v11, v89, v93
	v_and_b32_e32 v8, 0xffff, v8
	v_and_b32_e32 v10, 0xffff, v10
	v_lshl_or_b32 v178, v9, 16, v8
	v_lshl_or_b32 v179, v11, 16, v10
	global_store_dwordx2 v171, v[178:179], s[74:75] sc1
	v_cvt_pk_fp8_f32 v8, v66, v70
	v_cvt_pk_fp8_f32 v9, v74, v78
	v_cvt_pk_fp8_f32 v10, v82, v86
	v_cvt_pk_fp8_f32 v11, v90, v94
	v_and_b32_e32 v8, 0xffff, v8
	v_and_b32_e32 v10, 0xffff, v10
	v_lshl_or_b32 v180, v9, 16, v8
	v_lshl_or_b32 v181, v11, 16, v10
	global_store_dwordx2 v172, v[180:181], s[74:75] sc1
; #define LAS __attribute__((address_space(3)))
; __device__ __forceinline__ void transpose_item_fp8(const float* W, int N, unsigned char* W8, int pitch, int kofs, int k0, int n_src, int n_dst, float scale, LAS float* scr, int lane) {
;     const int r8 = lane >> 3, c4 = lane & 7;
;     f32x4 v[8];
; #pragma unroll
;     for (int i = 0; i < 8; ++i) v[i] = *(const f32x4*)(W + (size_t)(k0 + r8 + 8 * i) * N + n_src + 4 * c4);
; #pragma unroll
;     for (int i = 0; i < 8; ++i) { LAS float* d = scr + (r8 + 8 * i) * 33 + 4 * c4; d[0] = v[i][0]; d[1] = v[i][1]; d[2] = v[i][2]; d[3] = v[i][3]; }
;     asm volatile("s_waitcnt lgkmcnt(0)" ::: "memory");
;     const int n = lane & 31, cp = lane >> 5;
; #pragma unroll
;     for (int q = 0; q < 2; ++q) { const int ck = (2 * cp + q) * 16; const LAS float* sp = scr + ck * 33 + n; u32x4 o;
; #pragma unroll
;         for (int w = 0; w < 4; ++w) o[w] = pack_fp8x4(sp[(4 * w) * 33] * scale, sp[(4 * w + 1) * 33] * scale, sp[(4 * w + 2) * 33] * scale, sp[(4 * w + 3) * 33] * scale);
;         *(u32x4*)(W8 + (size_t)(n_dst + n) * pitch + kofs + k0 + ck) = o; }
; __global__ void __launch_bounds__(512, 2) hybrid_fwd(Args a) {
;     ...
;         constexpr int I_IN = (D / 64) * (DIN / 32);
;         for (int it = gw; it < I_IN; it += NGW) { const int nb = it % (DIN / 32), kb = it / (DIN / 32);
;             if ((a.fp8mask >> (nb >> 3)) & 1ull) transpose_item_fp8(a.w_in, DIN, (unsigned char*)WinT, 4096, 0, 64 * kb, gemm_col_to_orig(32 * nb), 32 * nb, W8_SCALE, scr, lane);
	v_cvt_pk_fp8_f32 v8, v67, v71
	v_cvt_pk_fp8_f32 v9, v75, v79
	v_cvt_pk_fp8_f32 v10, v83, v87
	v_cvt_pk_fp8_f32 v11, v91, v95
	v_and_b32_e32 v8, 0xffff, v8
	v_and_b32_e32 v10, 0xffff, v10
	v_lshl_or_b32 v182, v9, 16, v8
	v_lshl_or_b32 v183, v11, 16, v10
	global_store_dwordx2 v173, v[182:183], s[74:75] sc1
	s_add_u32 s47, s46, 0x800
	s_mul_hi_u32 s48, s47, 0xb60b61
	s_mul_i32 s49, s48, 0x168
	s_sub_u32 s49, s47, s49
	s_lshl_b32 s50, s48, 1
	s_or_b32 s50, s50, 1
	s_lshr_b32 s51, s49, 3
	s_and_b32 s52, s49, 7
	s_and_b32 s53, s52, 3
	s_lshr_b32 s54, s52, 2
	s_lshl_b32 s55, s53, 6
	s_lshl_b32 s56, s54, 5
	s_add_u32 s55, s55, s56
	s_bfe_u32 s56, s52, 0x10001
	s_lshl_b32 s56, s56, 7
	s_and_b32 s57, s52, 1
	s_lshl_b32 s57, s57, 5
	s_add_u32 s56, s56, s57
	s_lshl_b32 s57, s54, 6
	s_add_u32 s56, s56, s57
	s_lshl_b32 s57, s52, 5
	s_sub_u32 s58, s51, 9
	s_cmp_lt_u32 s58, 12
	s_cselect_b32 s57, s56, s57
	s_cmp_lt_u32 s51, 5
	s_cselect_b32 s57, s55, s57
	s_lshl_b32 s58, s51, 8
	s_add_u32 s57, s57, s58
	s_mul_i32 s58, s50, 0x2d0000
	s_lshl_b32 s57, s57, 2
	s_add_u32 s58, s58, s57
	s_add_u32 s60, s22, s58
	s_addc_u32 s61, s23, 0
	s_lshl_b32 s58, s49, 17
	s_lshl_b32 s59, s50, 6
	s_add_u32 s58, s58, s59
	s_add_u32 s74, s64, s58
	s_addc_u32 s75, s65, 0
	global_load_dwordx4 v[64:67], v162, s[60:61] nt
	global_load_dwordx4 v[68:71], v163, s[60:61] nt
	global_load_dwordx4 v[72:75], v164, s[60:61] nt
	global_load_dwordx4 v[76:79], v165, s[60:61] nt
	global_load_dwordx4 v[80:83], v166, s[60:61] nt
	global_load_dwordx4 v[84:87], v167, s[60:61] nt
	global_load_dwordx4 v[88:91], v168, s[60:61] nt
	global_load_dwordx4 v[92:95], v169, s[60:61] nt
	s_waitcnt vmcnt(20)
	v_pk_mul_f32 v[96:97], v[96:97], s[44:45]
	v_pk_mul_f32 v[98:99], v[98:99], s[44:45]
	v_pk_mul_f32 v[100:101], v[100:101], s[44:45]
	v_pk_mul_f32 v[102:103], v[102:103], s[44:45]
	v_pk_mul_f32 v[104:105], v[104:105], s[44:45]
	v_pk_mul_f32 v[106:107], v[106:107], s[44:45]
	v_pk_mul_f32 v[108:109], v[108:109], s[44:45]
	v_pk_mul_f32 v[110:111], v[110:111], s[44:45]
	v_pk_mul_f32 v[112:113], v[112:113], s[44:45]
	v_pk_mul_f32 v[114:115], v[114:115], s[44:45]
	v_pk_mul_f32 v[116:117], v[116:117], s[44:45]
	v_pk_mul_f32 v[118:119], v[118:119], s[44:45]
	v_pk_mul_f32 v[120:121], v[120:121], s[44:45]
	v_pk_mul_f32 v[122:123], v[122:123], s[44:45]
	v_pk_mul_f32 v[124:125], v[124:125], s[44:45]
	v_pk_mul_f32 v[126:127], v[126:127], s[44:45]
	v_cvt_pk_fp8_f32 v8, v96, v100
	v_cvt_pk_fp8_f32 v9, v104, v108
	v_cvt_pk_fp8_f32 v10, v112, v116
	v_cvt_pk_fp8_f32 v11, v120, v124
	v_and_b32_e32 v8, 0xffff, v8
	v_and_b32_e32 v10, 0xffff, v10
	v_lshl_or_b32 v184, v9, 16, v8
	v_lshl_or_b32 v185, v11, 16, v10
	global_store_dwordx2 v170, v[184:185], s[76:77] sc1
	v_cvt_pk_fp8_f32 v8, v97, v101
	v_cvt_pk_fp8_f32 v9, v105, v109
	v_cvt_pk_fp8_f32 v10, v113, v117
	v_cvt_pk_fp8_f32 v11, v121, v125
	v_and_b32_e32 v8, 0xffff, v8
	v_and_b32_e32 v10, 0xffff, v10
	v_lshl_or_b32 v186, v9, 16, v8
	v_lshl_or_b32 v187, v11, 16, v10
	global_store_dwordx2 v171, v[186:187], s[76:77] sc1
	v_cvt_pk_fp8_f32 v8, v98, v102
	v_cvt_pk_fp8_f32 v9, v106, v110
	v_cvt_pk_fp8_f32 v10, v114, v118
	v_cvt_pk_fp8_f32 v11, v122, v126
	v_and_b32_e32 v8, 0xffff, v8
	v_and_b32_e32 v10, 0xffff, v10
	v_lshl_or_b32 v188, v9, 16, v8
	v_lshl_or_b32 v189, v11, 16, v10
	global_store_dwordx2 v172, v[188:189], s[76:77] sc1
	v_cvt_pk_fp8_f32 v8, v99, v103
	v_cvt_pk_fp8_f32 v9, v107, v111
	v_cvt_pk_fp8_f32 v10, v115, v119
	v_cvt_pk_fp8_f32 v11, v123, v127
	v_and_b32_e32 v8, 0xffff, v8
	v_and_b32_e32 v10, 0xffff, v10
	v_lshl_or_b32 v190, v9, 16, v8
	v_lshl_or_b32 v191, v11, 16, v10
	global_store_dwordx2 v173, v[190:191], s[76:77] sc1
	s_add_u32 s47, s46, 0x1000
	s_mul_hi_u32 s48, s47, 0xb60b61
	s_mul_i32 s49, s48, 0x168
	s_sub_u32 s49, s47, s49
	s_lshl_b32 s50, s48, 1
	s_lshr_b32 s51, s49, 3
	s_and_b32 s52, s49, 7
	s_and_b32 s53, s52, 3
	s_lshr_b32 s54, s52, 2
	s_lshl_b32 s55, s53, 6
	s_lshl_b32 s56, s54, 5
	s_add_u32 s55, s55, s56
	s_bfe_u32 s56, s52, 0x10001
	s_lshl_b32 s56, s56, 7
	s_and_b32 s57, s52, 1
	s_lshl_b32 s57, s57, 5
	s_add_u32 s56, s56, s57
	s_lshl_b32 s57, s54, 6
	s_add_u32 s56, s56, s57
	s_lshl_b32 s57, s52, 5
	s_sub_u32 s58, s51, 9
	s_cmp_lt_u32 s58, 12
	s_cselect_b32 s57, s56, s57
	s_cmp_lt_u32 s51, 5
	s_cselect_b32 s57, s55, s57
	s_lshl_b32 s58, s51, 8
	s_add_u32 s57, s57, s58
	s_mul_i32 s58, s50, 0x2d0000
	s_lshl_b32 s57, s57, 2
	s_add_u32 s58, s58, s57
	s_add_u32 s60, s22, s58
	s_addc_u32 s61, s23, 0
	s_lshl_b32 s58, s49, 17
	s_lshl_b32 s59, s50, 6
	s_add_u32 s58, s58, s59
	s_add_u32 s76, s64, s58
	s_addc_u32 s77, s65, 0
	global_load_dwordx4 v[96:99], v162, s[60:61] nt
	global_load_dwordx4 v[100:103], v163, s[60:61] nt
	global_load_dwordx4 v[104:107], v164, s[60:61] nt
	global_load_dwordx4 v[108:111], v165, s[60:61] nt
	global_load_dwordx4 v[112:115], v166, s[60:61] nt
	global_load_dwordx4 v[116:119], v167, s[60:61] nt
	global_load_dwordx4 v[120:123], v168, s[60:61] nt
	global_load_dwordx4 v[124:127], v169, s[60:61] nt
	s_waitcnt vmcnt(24)
; #define LAS __attribute__((address_space(3)))
; __device__ __forceinline__ void transpose_item_fp8(const float* W, int N, unsigned char* W8, int pitch, int kofs, int k0, int n_src, int n_dst, float scale, LAS float* scr, int lane) {
;     const int r8 = lane >> 3, c4 = lane & 7;
;     f32x4 v[8];
; #pragma unroll
;     for (int i = 0; i < 8; ++i) v[i] = *(const f32x4*)(W + (size_t)(k0 + r8 + 8 * i) * N + n_src + 4 * c4);
; #pragma unroll
;     for (int i = 0; i < 8; ++i) { LAS float* d = scr + (r8 + 8 * i) * 33 + 4 * c4; d[0] = v[i][0]; d[1] = v[i][1]; d[2] = v[i][2]; d[3] = v[i][3]; }
;     asm volatile("s_waitcnt lgkmcnt(0)" ::: "memory");
;     const int n = lane & 31, cp = lane >> 5;
; #pragma unroll
;     for (int q = 0; q < 2; ++q) { const int ck = (2 * cp + q) * 16; const LAS float* sp = scr + ck * 33 + n; u32x4 o;
; #pragma unroll
;         for (int w = 0; w < 4; ++w) o[w] = pack_fp8x4(sp[(4 * w) * 33] * scale, sp[(4 * w + 1) * 33] * scale, sp[(4 * w + 2) * 33] * scale, sp[(4 * w + 3) * 33] * scale);
;         *(u32x4*)(W8 + (size_t)(n_dst + n) * pitch + kofs + k0 + ck) = o; }
; __global__ void __launch_bounds__(512, 2) hybrid_fwd(Args a) {
;     ...
;         constexpr int I_IN = (D / 64) * (DIN / 32);
;         for (int it = gw; it < I_IN; it += NGW) { const int nb = it % (DIN / 32), kb = it / (DIN / 32);
;             if ((a.fp8mask >> (nb >> 3)) & 1ull) transpose_item_fp8(a.w_in, DIN, (unsigned char*)WinT, 4096, 0, 64 * kb, gemm_col_to_orig(32 * nb), 32 * nb, W8_SCALE, scr, lane);
	v_pk_mul_f32 v[128:129], v[128:129], s[44:45]
	v_pk_mul_f32 v[130:131], v[130:131], s[44:45]
	v_pk_mul_f32 v[132:133], v[132:133], s[44:45]
	v_pk_mul_f32 v[134:135], v[134:135], s[44:45]
	v_pk_mul_f32 v[136:137], v[136:137], s[44:45]
	v_pk_mul_f32 v[138:139], v[138:139], s[44:45]
	v_pk_mul_f32 v[140:141], v[140:141], s[44:45]
	v_pk_mul_f32 v[142:143], v[142:143], s[44:45]
	v_pk_mul_f32 v[144:145], v[144:145], s[44:45]
	v_pk_mul_f32 v[146:147], v[146:147], s[44:45]
	v_pk_mul_f32 v[148:149], v[148:149], s[44:45]
	v_pk_mul_f32 v[150:151], v[150:151], s[44:45]
	v_pk_mul_f32 v[152:153], v[152:153], s[44:45]
	v_pk_mul_f32 v[154:155], v[154:155], s[44:45]
	v_pk_mul_f32 v[156:157], v[156:157], s[44:45]
	v_pk_mul_f32 v[158:159], v[158:159], s[44:45]
	v_cvt_pk_fp8_f32 v8, v128, v132
	v_cvt_pk_fp8_f32 v9, v136, v140
	v_cvt_pk_fp8_f32 v10, v144, v148
	v_cvt_pk_fp8_f32 v11, v152, v156
	v_and_b32_e32 v8, 0xffff, v8
	v_and_b32_e32 v10, 0xffff, v10
	v_lshl_or_b32 v176, v9, 16, v8
	v_lshl_or_b32 v177, v11, 16, v10
	global_store_dwordx2 v170, v[176:177], s[78:79] sc1
	v_cvt_pk_fp8_f32 v8, v129, v133
	v_cvt_pk_fp8_f32 v9, v137, v141
	v_cvt_pk_fp8_f32 v10, v145, v149
	v_cvt_pk_fp8_f32 v11, v153, v157
	v_and_b32_e32 v8, 0xffff, v8
	v_and_b32_e32 v10, 0xffff, v10
	v_lshl_or_b32 v178, v9, 16, v8
	v_lshl_or_b32 v179, v11, 16, v10
	global_store_dwordx2 v171, v[178:179], s[78:79] sc1
	v_cvt_pk_fp8_f32 v8, v130, v134
	v_cvt_pk_fp8_f32 v9, v138, v142
	v_cvt_pk_fp8_f32 v10, v146, v150
	v_cvt_pk_fp8_f32 v11, v154, v158
	v_and_b32_e32 v8, 0xffff, v8
	v_and_b32_e32 v10, 0xffff, v10
	v_lshl_or_b32 v180, v9, 16, v8
	v_lshl_or_b32 v181, v11, 16, v10
	global_store_dwordx2 v172, v[180:181], s[78:79] sc1
	v_cvt_pk_fp8_f32 v8, v131, v135
	v_cvt_pk_fp8_f32 v9, v139, v143
	v_cvt_pk_fp8_f32 v10, v147, v151
	v_cvt_pk_fp8_f32 v11, v155, v159
	v_and_b32_e32 v8, 0xffff, v8
	v_and_b32_e32 v10, 0xffff, v10
	v_lshl_or_b32 v182, v9, 16, v8
	v_lshl_or_b32 v183, v11, 16, v10
	global_store_dwordx2 v173, v[182:183], s[78:79] sc1
	s_add_u32 s47, s46, 0x1000
	s_mul_hi_u32 s48, s47, 0xb60b61
	s_mul_i32 s49, s48, 0x168
	s_sub_u32 s49, s47, s49
	s_lshl_b32 s50, s48, 1
	s_or_b32 s50, s50, 1
	s_lshr_b32 s51, s49, 3
	s_and_b32 s52, s49, 7
	s_and_b32 s53, s52, 3
	s_lshr_b32 s54, s52, 2
	s_lshl_b32 s55, s53, 6
	s_lshl_b32 s56, s54, 5
	s_add_u32 s55, s55, s56
	s_bfe_u32 s56, s52, 0x10001
	s_lshl_b32 s56, s56, 7
	s_and_b32 s57, s52, 1
	s_lshl_b32 s57, s57, 5
	s_add_u32 s56, s56, s57
	s_lshl_b32 s57, s54, 6
	s_add_u32 s56, s56, s57
	s_lshl_b32 s57, s52, 5
	s_sub_u32 s58, s51, 9
	s_cmp_lt_u32 s58, 12
	s_cselect_b32 s57, s56, s57
	s_cmp_lt_u32 s51, 5
	s_cselect_b32 s57, s55, s57
	s_lshl_b32 s58, s51, 8
	s_add_u32 s57, s57, s58
	s_mul_i32 s58, s50, 0x2d0000
	s_lshl_b32 s57, s57, 2
	s_add_u32 s58, s58, s57
	s_add_u32 s60, s22, s58
	s_addc_u32 s61, s23, 0
	s_lshl_b32 s58, s49, 17
	s_lshl_b32 s59, s50, 6
	s_add_u32 s58, s58, s59
	s_add_u32 s78, s64, s58
	s_addc_u32 s79, s65, 0
	global_load_dwordx4 v[128:131], v162, s[60:61] nt
	global_load_dwordx4 v[132:135], v163, s[60:61] nt
	global_load_dwordx4 v[136:139], v164, s[60:61] nt
	global_load_dwordx4 v[140:143], v165, s[60:61] nt
	global_load_dwordx4 v[144:147], v166, s[60:61] nt
	global_load_dwordx4 v[148:151], v167, s[60:61] nt
	global_load_dwordx4 v[152:155], v168, s[60:61] nt
	global_load_dwordx4 v[156:159], v169, s[60:61] nt
	s_waitcnt vmcnt(24)
	v_pk_mul_f32 v[64:65], v[64:65], s[44:45]
	v_pk_mul_f32 v[66:67], v[66:67], s[44:45]
	v_pk_mul_f32 v[68:69], v[68:69], s[44:45]
	v_pk_mul_f32 v[70:71], v[70:71], s[44:45]
	v_pk_mul_f32 v[72:73], v[72:73], s[44:45]
	v_pk_mul_f32 v[74:75], v[74:75], s[44:45]
	v_pk_mul_f32 v[76:77], v[76:77], s[44:45]
	v_pk_mul_f32 v[78:79], v[78:79], s[44:45]
	v_pk_mul_f32 v[80:81], v[80:81], s[44:45]
	v_pk_mul_f32 v[82:83], v[82:83], s[44:45]
	v_pk_mul_f32 v[84:85], v[84:85], s[44:45]
	v_pk_mul_f32 v[86:87], v[86:87], s[44:45]
	v_pk_mul_f32 v[88:89], v[88:89], s[44:45]
	v_pk_mul_f32 v[90:91], v[90:91], s[44:45]
	v_pk_mul_f32 v[92:93], v[92:93], s[44:45]
	v_pk_mul_f32 v[94:95], v[94:95], s[44:45]
	v_cvt_pk_fp8_f32 v8, v64, v68
	v_cvt_pk_fp8_f32 v9, v72, v76
	v_cvt_pk_fp8_f32 v10, v80, v84
	v_cvt_pk_fp8_f32 v11, v88, v92
	v_and_b32_e32 v8, 0xffff, v8
	v_and_b32_e32 v10, 0xffff, v10
	v_lshl_or_b32 v184, v9, 16, v8
	v_lshl_or_b32 v185, v11, 16, v10
	global_store_dwordx2 v170, v[184:185], s[74:75] sc1
	v_cvt_pk_fp8_f32 v8, v65, v69
	v_cvt_pk_fp8_f32 v9, v73, v77
	v_cvt_pk_fp8_f32 v10, v81, v85
	v_cvt_pk_fp8_f32 v11, v89, v93
	v_and_b32_e32 v8, 0xffff, v8
	v_and_b32_e32 v10, 0xffff, v10
	v_lshl_or_b32 v186, v9, 16, v8
	v_lshl_or_b32 v187, v11, 16, v10
	global_store_dwordx2 v171, v[186:187], s[74:75] sc1
	v_cvt_pk_fp8_f32 v8, v66, v70
	v_cvt_pk_fp8_f32 v9, v74, v78
	v_cvt_pk_fp8_f32 v10, v82, v86
	v_cvt_pk_fp8_f32 v11, v90, v94
	v_and_b32_e32 v8, 0xffff, v8
	v_and_b32_e32 v10, 0xffff, v10
	v_lshl_or_b32 v188, v9, 16, v8
	v_lshl_or_b32 v189, v11, 16, v10
	global_store_dwordx2 v172, v[188:189], s[74:75] sc1
	v_cvt_pk_fp8_f32 v8, v67, v71
	v_cvt_pk_fp8_f32 v9, v75, v79
	v_cvt_pk_fp8_f32 v10, v83, v87
	v_cvt_pk_fp8_f32 v11, v91, v95
	v_and_b32_e32 v8, 0xffff, v8
	v_and_b32_e32 v10, 0xffff, v10
	v_lshl_or_b32 v190, v9, 16, v8
	v_lshl_or_b32 v191, v11, 16, v10
	global_store_dwordx2 v173, v[190:191], s[74:75] sc1
	s_waitcnt vmcnt(16)
; #define LAS __attribute__((address_space(3)))
; __device__ __forceinline__ void transpose_item_fp8(const float* W, int N, unsigned char* W8, int pitch, int kofs, int k0, int n_src, int n_dst, float scale, LAS float* scr, int lane) {
;     const int r8 = lane >> 3, c4 = lane & 7;
;     f32x4 v[8];
; #pragma unroll
;     for (int i = 0; i < 8; ++i) v[i] = *(const f32x4*)(W + (size_t)(k0 + r8 + 8 * i) * N + n_src + 4 * c4);
; #pragma unroll
;     for (int i = 0; i < 8; ++i) { LAS float* d = scr + (r8 + 8 * i) * 33 + 4 * c4; d[0] = v[i][0]; d[1] = v[i][1]; d[2] = v[i][2]; d[3] = v[i][3]; }
;     asm volatile("s_waitcnt lgkmcnt(0)" ::: "memory");
;     const int n = lane & 31, cp = lane >> 5;
; #pragma unroll
;     for (int q = 0; q < 2; ++q) { const int ck = (2 * cp + q) * 16; const LAS float* sp = scr + ck * 33 + n; u32x4 o;
; #pragma unroll
;         for (int w = 0; w < 4; ++w) o[w] = pack_fp8x4(sp[(4 * w) * 33] * scale, sp[(4 * w + 1) * 33] * scale, sp[(4 * w + 2) * 33] * scale, sp[(4 * w + 3) * 33] * scale);
;         *(u32x4*)(W8 + (size_t)(n_dst + n) * pitch + kofs + k0 + ck) = o; }
; __global__ void __launch_bounds__(512, 2) hybrid_fwd(Args a) {
;     ...
;         constexpr int I_IN = (D / 64) * (DIN / 32);
;         for (int it = gw; it < I_IN; it += NGW) { const int nb = it % (DIN / 32), kb = it / (DIN / 32);
;             if ((a.fp8mask >> (nb >> 3)) & 1ull) transpose_item_fp8(a.w_in, DIN, (unsigned char*)WinT, 4096, 0, 64 * kb, gemm_col_to_orig(32 * nb), 32 * nb, W8_SCALE, scr, lane);
	v_pk_mul_f32 v[96:97], v[96:97], s[44:45]
	v_pk_mul_f32 v[98:99], v[98:99], s[44:45]
	v_pk_mul_f32 v[100:101], v[100:101], s[44:45]
	v_pk_mul_f32 v[102:103], v[102:103], s[44:45]
	v_pk_mul_f32 v[104:105], v[104:105], s[44:45]
	v_pk_mul_f32 v[106:107], v[106:107], s[44:45]
	v_pk_mul_f32 v[108:109], v[108:109], s[44:45]
	v_pk_mul_f32 v[110:111], v[110:111], s[44:45]
	v_pk_mul_f32 v[112:113], v[112:113], s[44:45]
	v_pk_mul_f32 v[114:115], v[114:115], s[44:45]
	v_pk_mul_f32 v[116:117], v[116:117], s[44:45]
	v_pk_mul_f32 v[118:119], v[118:119], s[44:45]
	v_pk_mul_f32 v[120:121], v[120:121], s[44:45]
	v_pk_mul_f32 v[122:123], v[122:123], s[44:45]
	v_pk_mul_f32 v[124:125], v[124:125], s[44:45]
	v_pk_mul_f32 v[126:127], v[126:127], s[44:45]
	v_cvt_pk_fp8_f32 v8, v96, v100
	v_cvt_pk_fp8_f32 v9, v104, v108
	v_cvt_pk_fp8_f32 v10, v112, v116
	v_cvt_pk_fp8_f32 v11, v120, v124
	v_and_b32_e32 v8, 0xffff, v8
	v_and_b32_e32 v10, 0xffff, v10
	v_lshl_or_b32 v176, v9, 16, v8
	v_lshl_or_b32 v177, v11, 16, v10
	global_store_dwordx2 v170, v[176:177], s[76:77] sc1
	v_cvt_pk_fp8_f32 v8, v97, v101
	v_cvt_pk_fp8_f32 v9, v105, v109
	v_cvt_pk_fp8_f32 v10, v113, v117
	v_cvt_pk_fp8_f32 v11, v121, v125
	v_and_b32_e32 v8, 0xffff, v8
	v_and_b32_e32 v10, 0xffff, v10
	v_lshl_or_b32 v178, v9, 16, v8
	v_lshl_or_b32 v179, v11, 16, v10
	global_store_dwordx2 v171, v[178:179], s[76:77] sc1
	v_cvt_pk_fp8_f32 v8, v98, v102
	v_cvt_pk_fp8_f32 v9, v106, v110
	v_cvt_pk_fp8_f32 v10, v114, v118
	v_cvt_pk_fp8_f32 v11, v122, v126
	v_and_b32_e32 v8, 0xffff, v8
	v_and_b32_e32 v10, 0xffff, v10
	v_lshl_or_b32 v180, v9, 16, v8
	v_lshl_or_b32 v181, v11, 16, v10
	global_store_dwordx2 v172, v[180:181], s[76:77] sc1
	v_cvt_pk_fp8_f32 v8, v99, v103
	v_cvt_pk_fp8_f32 v9, v107, v111
	v_cvt_pk_fp8_f32 v10, v115, v119
	v_cvt_pk_fp8_f32 v11, v123, v127
	v_and_b32_e32 v8, 0xffff, v8
	v_and_b32_e32 v10, 0xffff, v10
	v_lshl_or_b32 v182, v9, 16, v8
	v_lshl_or_b32 v183, v11, 16, v10
	global_store_dwordx2 v173, v[182:183], s[76:77] sc1
	s_waitcnt vmcnt(8)
	v_pk_mul_f32 v[128:129], v[128:129], s[44:45]
	v_pk_mul_f32 v[130:131], v[130:131], s[44:45]
	v_pk_mul_f32 v[132:133], v[132:133], s[44:45]
	v_pk_mul_f32 v[134:135], v[134:135], s[44:45]
	v_pk_mul_f32 v[136:137], v[136:137], s[44:45]
	v_pk_mul_f32 v[138:139], v[138:139], s[44:45]
	v_pk_mul_f32 v[140:141], v[140:141], s[44:45]
	v_pk_mul_f32 v[142:143], v[142:143], s[44:45]
	v_pk_mul_f32 v[144:145], v[144:145], s[44:45]
	v_pk_mul_f32 v[146:147], v[146:147], s[44:45]
	v_pk_mul_f32 v[148:149], v[148:149], s[44:45]
	v_pk_mul_f32 v[150:151], v[150:151], s[44:45]
	v_pk_mul_f32 v[152:153], v[152:153], s[44:45]
	v_pk_mul_f32 v[154:155], v[154:155], s[44:45]
	v_pk_mul_f32 v[156:157], v[156:157], s[44:45]
	v_pk_mul_f32 v[158:159], v[158:159], s[44:45]
	v_cvt_pk_fp8_f32 v8, v128, v132
	v_cvt_pk_fp8_f32 v9, v136, v140
	v_cvt_pk_fp8_f32 v10, v144, v148
	v_cvt_pk_fp8_f32 v11, v152, v156
	v_and_b32_e32 v8, 0xffff, v8
	v_and_b32_e32 v10, 0xffff, v10
	v_lshl_or_b32 v184, v9, 16, v8
	v_lshl_or_b32 v185, v11, 16, v10
	global_store_dwordx2 v170, v[184:185], s[78:79] sc1
	v_cvt_pk_fp8_f32 v8, v129, v133
	v_cvt_pk_fp8_f32 v9, v137, v141
	v_cvt_pk_fp8_f32 v10, v145, v149
	v_cvt_pk_fp8_f32 v11, v153, v157
	v_and_b32_e32 v8, 0xffff, v8
	v_and_b32_e32 v10, 0xffff, v10
	v_lshl_or_b32 v186, v9, 16, v8
	v_lshl_or_b32 v187, v11, 16, v10
	global_store_dwordx2 v171, v[186:187], s[78:79] sc1
	v_cvt_pk_fp8_f32 v8, v130, v134
	v_cvt_pk_fp8_f32 v9, v138, v142
	v_cvt_pk_fp8_f32 v10, v146, v150
	v_cvt_pk_fp8_f32 v11, v154, v158
	v_and_b32_e32 v8, 0xffff, v8
	v_and_b32_e32 v10, 0xffff, v10
	v_lshl_or_b32 v188, v9, 16, v8
	v_lshl_or_b32 v189, v11, 16, v10
	global_store_dwordx2 v172, v[188:189], s[78:79] sc1
	v_cvt_pk_fp8_f32 v8, v131, v135
	v_cvt_pk_fp8_f32 v9, v139, v143
	v_cvt_pk_fp8_f32 v10, v147, v151
	v_cvt_pk_fp8_f32 v11, v155, v159
	v_and_b32_e32 v8, 0xffff, v8
	v_and_b32_e32 v10, 0xffff, v10
	v_lshl_or_b32 v190, v9, 16, v8
	v_lshl_or_b32 v191, v11, 16, v10
	global_store_dwordx2 v173, v[190:191], s[78:79] sc1
	s_branch .Lp0c_end
.Lp0c_four:
	s_add_u32 s47, s46, 0x0
	s_mul_hi_u32 s48, s47, 0xb60b61
	s_mul_i32 s49, s48, 0x168
	s_sub_u32 s49, s47, s49
	s_lshl_b32 s50, s48, 1
	s_lshr_b32 s51, s49, 3
	s_and_b32 s52, s49, 7
	s_and_b32 s53, s52, 3
	s_lshr_b32 s54, s52, 2
	s_lshl_b32 s55, s53, 6
	s_lshl_b32 s56, s54, 5
	s_add_u32 s55, s55, s56
	s_bfe_u32 s56, s52, 0x10001
	s_lshl_b32 s56, s56, 7
	s_and_b32 s57, s52, 1
	s_lshl_b32 s57, s57, 5
	s_add_u32 s56, s56, s57
	s_lshl_b32 s57, s54, 6
	s_add_u32 s56, s56, s57
	s_lshl_b32 s57, s52, 5
	s_sub_u32 s58, s51, 9
	s_cmp_lt_u32 s58, 12
	s_cselect_b32 s57, s56, s57
	s_cmp_lt_u32 s51, 5
	s_cselect_b32 s57, s55, s57
	s_lshl_b32 s58, s51, 8
	s_add_u32 s57, s57, s58
	s_mul_i32 s58, s50, 0x2d0000
	s_lshl_b32 s57, s57, 2
	s_add_u32 s58, s58, s57
	s_add_u32 s60, s22, s58
	s_addc_u32 s61, s23, 0
	s_lshl_b32 s58, s49, 17
	s_lshl_b32 s59, s50, 6
	s_add_u32 s58, s58, s59
	s_add_u32 s74, s64, s58
	s_addc_u32 s75, s65, 0
	global_load_dwordx4 v[64:67], v162, s[60:61] nt
	global_load_dwordx4 v[68:71], v163, s[60:61] nt
	global_load_dwordx4 v[72:75], v164, s[60:61] nt
	global_load_dwordx4 v[76:79], v165, s[60:61] nt
	global_load_dwordx4 v[80:83], v166, s[60:61] nt
	global_load_dwordx4 v[84:87], v167, s[60:61] nt
	global_load_dwordx4 v[88:91], v168, s[60:61] nt
	global_load_dwordx4 v[92:95], v169, s[60:61] nt
	s_add_u32 s47, s46, 0x0
	s_mul_hi_u32 s48, s47, 0xb60b61
	s_mul_i32 s49, s48, 0x168
	s_sub_u32 s49, s47, s49
	s_lshl_b32 s50, s48, 1
	s_or_b32 s50, s50, 1
	s_lshr_b32 s51, s49, 3
	s_and_b32 s52, s49, 7
	s_and_b32 s53, s52, 3
	s_lshr_b32 s54, s52, 2
; #define LAS __attribute__((address_space(3)))
; __device__ __forceinline__ void transpose_item_fp8(const float* W, int N, unsigned char* W8, int pitch, int kofs, int k0, int n_src, int n_dst, float scale, LAS float* scr, int lane) {
;     const int r8 = lane >> 3, c4 = lane & 7;
;     f32x4 v[8];
; #pragma unroll
;     for (int i = 0; i < 8; ++i) v[i] = *(const f32x4*)(W + (size_t)(k0 + r8 + 8 * i) * N + n_src + 4 * c4);
; #pragma unroll
;     for (int i = 0; i < 8; ++i) { LAS float* d = scr + (r8 + 8 * i) * 33 + 4 * c4; d[0] = v[i][0]; d[1] = v[i][1]; d[2] = v[i][2]; d[3] = v[i][3]; }
;     asm volatile("s_waitcnt lgkmcnt(0)" ::: "memory");
;     const int n = lane & 31, cp = lane >> 5;
; #pragma unroll
;     for (int q = 0; q < 2; ++q) { const int ck = (2 * cp + q) * 16; const LAS float* sp = scr + ck * 33 + n; u32x4 o;
; #pragma unroll
;         for (int w = 0; w < 4; ++w) o[w] = pack_fp8x4(sp[(4 * w) * 33] * scale, sp[(4 * w + 1) * 33] * scale, sp[(4 * w + 2) * 33] * scale, sp[(4 * w + 3) * 33] * scale);
;         *(u32x4*)(W8 + (size_t)(n_dst + n) * pitch + kofs + k0 + ck) = o; }
; __global__ void __launch_bounds__(512, 2) hybrid_fwd(Args a) {
;     ...
;         constexpr int I_IN = (D / 64) * (DIN / 32);
;         for (int it = gw; it < I_IN; it += NGW) { const int nb = it % (DIN / 32), kb = it / (DIN / 32);
;             if ((a.fp8mask >> (nb >> 3)) & 1ull) transpose_item_fp8(a.w_in, DIN, (unsigned char*)WinT, 4096, 0, 64 * kb, gemm_col_to_orig(32 * nb), 32 * nb, W8_SCALE, scr, lane);
	s_lshl_b32 s55, s53, 6
	s_lshl_b32 s56, s54, 5
	s_add_u32 s55, s55, s56
	s_bfe_u32 s56, s52, 0x10001
	s_lshl_b32 s56, s56, 7
	s_and_b32 s57, s52, 1
	s_lshl_b32 s57, s57, 5
	s_add_u32 s56, s56, s57
	s_lshl_b32 s57, s54, 6
	s_add_u32 s56, s56, s57
	s_lshl_b32 s57, s52, 5
	s_sub_u32 s58, s51, 9
	s_cmp_lt_u32 s58, 12
	s_cselect_b32 s57, s56, s57
	s_cmp_lt_u32 s51, 5
	s_cselect_b32 s57, s55, s57
	s_lshl_b32 s58, s51, 8
	s_add_u32 s57, s57, s58
	s_mul_i32 s58, s50, 0x2d0000
	s_lshl_b32 s57, s57, 2
	s_add_u32 s58, s58, s57
	s_add_u32 s60, s22, s58
	s_addc_u32 s61, s23, 0
	s_lshl_b32 s58, s49, 17
	s_lshl_b32 s59, s50, 6
	s_add_u32 s58, s58, s59
	s_add_u32 s76, s64, s58
	s_addc_u32 s77, s65, 0
	global_load_dwordx4 v[96:99], v162, s[60:61] nt
	global_load_dwordx4 v[100:103], v163, s[60:61] nt
	global_load_dwordx4 v[104:107], v164, s[60:61] nt
	global_load_dwordx4 v[108:111], v165, s[60:61] nt
	global_load_dwordx4 v[112:115], v166, s[60:61] nt
	global_load_dwordx4 v[116:119], v167, s[60:61] nt
	global_load_dwordx4 v[120:123], v168, s[60:61] nt
	global_load_dwordx4 v[124:127], v169, s[60:61] nt
	s_add_u32 s47, s46, 0x800
	s_mul_hi_u32 s48, s47, 0xb60b61
	s_mul_i32 s49, s48, 0x168
	s_sub_u32 s49, s47, s49
	s_lshl_b32 s50, s48, 1
	s_lshr_b32 s51, s49, 3
	s_and_b32 s52, s49, 7
	s_and_b32 s53, s52, 3
	s_lshr_b32 s54, s52, 2
	s_lshl_b32 s55, s53, 6
	s_lshl_b32 s56, s54, 5
	s_add_u32 s55, s55, s56
	s_bfe_u32 s56, s52, 0x10001
	s_lshl_b32 s56, s56, 7
	s_and_b32 s57, s52, 1
	s_lshl_b32 s57, s57, 5
	s_add_u32 s56, s56, s57
	s_lshl_b32 s57, s54, 6
	s_add_u32 s56, s56, s57
	s_lshl_b32 s57, s52, 5
	s_sub_u32 s58, s51, 9
	s_cmp_lt_u32 s58, 12
	s_cselect_b32 s57, s56, s57
	s_cmp_lt_u32 s51, 5
	s_cselect_b32 s57, s55, s57
	s_lshl_b32 s58, s51, 8
	s_add_u32 s57, s57, s58
	s_mul_i32 s58, s50, 0x2d0000
	s_lshl_b32 s57, s57, 2
	s_add_u32 s58, s58, s57
	s_add_u32 s60, s22, s58
	s_addc_u32 s61, s23, 0
	s_lshl_b32 s58, s49, 17
	s_lshl_b32 s59, s50, 6
	s_add_u32 s58, s58, s59
	s_add_u32 s78, s64, s58
	s_addc_u32 s79, s65, 0
	global_load_dwordx4 v[128:131], v162, s[60:61] nt
	global_load_dwordx4 v[132:135], v163, s[60:61] nt
	global_load_dwordx4 v[136:139], v164, s[60:61] nt
	global_load_dwordx4 v[140:143], v165, s[60:61] nt
	global_load_dwordx4 v[144:147], v166, s[60:61] nt
	global_load_dwordx4 v[148:151], v167, s[60:61] nt
	global_load_dwordx4 v[152:155], v168, s[60:61] nt
	global_load_dwordx4 v[156:159], v169, s[60:61] nt
	s_waitcnt vmcnt(16)
	v_pk_mul_f32 v[64:65], v[64:65], s[44:45]
	v_pk_mul_f32 v[66:67], v[66:67], s[44:45]
	v_pk_mul_f32 v[68:69], v[68:69], s[44:45]
	v_pk_mul_f32 v[70:71], v[70:71], s[44:45]
	v_pk_mul_f32 v[72:73], v[72:73], s[44:45]
	v_pk_mul_f32 v[74:75], v[74:75], s[44:45]
	v_pk_mul_f32 v[76:77], v[76:77], s[44:45]
	v_pk_mul_f32 v[78:79], v[78:79], s[44:45]
	v_pk_mul_f32 v[80:81], v[80:81], s[44:45]
	v_pk_mul_f32 v[82:83], v[82:83], s[44:45]
	v_pk_mul_f32 v[84:85], v[84:85], s[44:45]
	v_pk_mul_f32 v[86:87], v[86:87], s[44:45]
	v_pk_mul_f32 v[88:89], v[88:89], s[44:45]
	v_pk_mul_f32 v[90:91], v[90:91], s[44:45]
	v_pk_mul_f32 v[92:93], v[92:93], s[44:45]
	v_pk_mul_f32 v[94:95], v[94:95], s[44:45]
	v_cvt_pk_fp8_f32 v8, v64, v68
	v_cvt_pk_fp8_f32 v9, v72, v76
	v_cvt_pk_fp8_f32 v10, v80, v84
	v_cvt_pk_fp8_f32 v11, v88, v92
	v_and_b32_e32 v8, 0xffff, v8
	v_and_b32_e32 v10, 0xffff, v10
	v_lshl_or_b32 v176, v9, 16, v8
	v_lshl_or_b32 v177, v11, 16, v10
	global_store_dwordx2 v170, v[176:177], s[74:75] sc1
	v_cvt_pk_fp8_f32 v8, v65, v69
	v_cvt_pk_fp8_f32 v9, v73, v77
	v_cvt_pk_fp8_f32 v10, v81, v85
	v_cvt_pk_fp8_f32 v11, v89, v93
	v_and_b32_e32 v8, 0xffff, v8
	v_and_b32_e32 v10, 0xffff, v10
	v_lshl_or_b32 v178, v9, 16, v8
	v_lshl_or_b32 v179, v11, 16, v10
	global_store_dwordx2 v171, v[178:179], s[74:75] sc1
	v_cvt_pk_fp8_f32 v8, v66, v70
	v_cvt_pk_fp8_f32 v9, v74, v78
	v_cvt_pk_fp8_f32 v10, v82, v86
	v_cvt_pk_fp8_f32 v11, v90, v94
	v_and_b32_e32 v8, 0xffff, v8
	v_and_b32_e32 v10, 0xffff, v10
	v_lshl_or_b32 v180, v9, 16, v8
	v_lshl_or_b32 v181, v11, 16, v10
	global_store_dwordx2 v172, v[180:181], s[74:75] sc1
	v_cvt_pk_fp8_f32 v8, v67, v71
	v_cvt_pk_fp8_f32 v9, v75, v79
	v_cvt_pk_fp8_f32 v10, v83, v87
	v_cvt_pk_fp8_f32 v11, v91, v95
	v_and_b32_e32 v8, 0xffff, v8
	v_and_b32_e32 v10, 0xffff, v10
	v_lshl_or_b32 v182, v9, 16, v8
	v_lshl_or_b32 v183, v11, 16, v10
	global_store_dwordx2 v173, v[182:183], s[74:75] sc1
	s_add_u32 s47, s46, 0x800
	s_mul_hi_u32 s48, s47, 0xb60b61
	s_mul_i32 s49, s48, 0x168
	s_sub_u32 s49, s47, s49
	s_lshl_b32 s50, s48, 1
	s_or_b32 s50, s50, 1
	s_lshr_b32 s51, s49, 3
	s_and_b32 s52, s49, 7
	s_and_b32 s53, s52, 3
	s_lshr_b32 s54, s52, 2
	s_lshl_b32 s55, s53, 6
	s_lshl_b32 s56, s54, 5
	s_add_u32 s55, s55, s56
	s_bfe_u32 s56, s52, 0x10001
	s_lshl_b32 s56, s56, 7
	s_and_b32 s57, s52, 1
	s_lshl_b32 s57, s57, 5
	s_add_u32 s56, s56, s57
	s_lshl_b32 s57, s54, 6
	s_add_u32 s56, s56, s57
	s_lshl_b32 s57, s52, 5
	s_sub_u32 s58, s51, 9
	s_cmp_lt_u32 s58, 12
	s_cselect_b32 s57, s56, s57
	s_cmp_lt_u32 s51, 5
	s_cselect_b32 s57, s55, s57
	s_lshl_b32 s58, s51, 8
	s_add_u32 s57, s57, s58
	s_mul_i32 s58, s50, 0x2d0000
	s_lshl_b32 s57, s57, 2
	s_add_u32 s58, s58, s57
	s_add_u32 s60, s22, s58
	s_addc_u32 s61, s23, 0
	s_lshl_b32 s58, s49, 17
	s_lshl_b32 s59, s50, 6
	s_add_u32 s58, s58, s59
	s_add_u32 s74, s64, s58
	s_addc_u32 s75, s65, 0
	global_load_dwordx4 v[64:67], v162, s[60:61] nt
	global_load_dwordx4 v[68:71], v163, s[60:61] nt
	global_load_dwordx4 v[72:75], v164, s[60:61] nt
	global_load_dwordx4 v[76:79], v165, s[60:61] nt
	global_load_dwordx4 v[80:83], v166, s[60:61] nt
	global_load_dwordx4 v[84:87], v167, s[60:61] nt
	global_load_dwordx4 v[88:91], v168, s[60:61] nt
	global_load_dwordx4 v[92:95], v169, s[60:61] nt
	s_waitcnt vmcnt(20)
; #define LAS __attribute__((address_space(3)))
; __device__ __forceinline__ void transpose_item_fp8(const float* W, int N, unsigned char* W8, int pitch, int kofs, int k0, int n_src, int n_dst, float scale, LAS float* scr, int lane) {
;     const int r8 = lane >> 3, c4 = lane & 7;
;     f32x4 v[8];
; #pragma unroll
;     for (int i = 0; i < 8; ++i) v[i] = *(const f32x4*)(W + (size_t)(k0 + r8 + 8 * i) * N + n_src + 4 * c4);
; #pragma unroll
;     for (int i = 0; i < 8; ++i) { LAS float* d = scr + (r8 + 8 * i) * 33 + 4 * c4; d[0] = v[i][0]; d[1] = v[i][1]; d[2] = v[i][2]; d[3] = v[i][3]; }
;     asm volatile("s_waitcnt lgkmcnt(0)" ::: "memory");
;     const int n = lane & 31, cp = lane >> 5;
; #pragma unroll
;     for (int q = 0; q < 2; ++q) { const int ck = (2 * cp + q) * 16; const LAS float* sp = scr + ck * 33 + n; u32x4 o;
; #pragma unroll
;         for (int w = 0; w < 4; ++w) o[w] = pack_fp8x4(sp[(4 * w) * 33] * scale, sp[(4 * w + 1) * 33] * scale, sp[(4 * w + 2) * 33] * scale, sp[(4 * w + 3) * 33] * scale);
;         *(u32x4*)(W8 + (size_t)(n_dst + n) * pitch + kofs + k0 + ck) = o; }
; __global__ void __launch_bounds__(512, 2) hybrid_fwd(Args a) {
;     ...
;         constexpr int I_IN = (D / 64) * (DIN / 32);
;         for (int it = gw; it < I_IN; it += NGW) { const int nb = it % (DIN / 32), kb = it / (DIN / 32);
;             if ((a.fp8mask >> (nb >> 3)) & 1ull) transpose_item_fp8(a.w_in, DIN, (unsigned char*)WinT, 4096, 0, 64 * kb, gemm_col_to_orig(32 * nb), 32 * nb, W8_SCALE, scr, lane);
	v_pk_mul_f32 v[96:97], v[96:97], s[44:45]
	v_pk_mul_f32 v[98:99], v[98:99], s[44:45]
	v_pk_mul_f32 v[100:101], v[100:101], s[44:45]
	v_pk_mul_f32 v[102:103], v[102:103], s[44:45]
	v_pk_mul_f32 v[104:105], v[104:105], s[44:45]
	v_pk_mul_f32 v[106:107], v[106:107], s[44:45]
	v_pk_mul_f32 v[108:109], v[108:109], s[44:45]
	v_pk_mul_f32 v[110:111], v[110:111], s[44:45]
	v_pk_mul_f32 v[112:113], v[112:113], s[44:45]
	v_pk_mul_f32 v[114:115], v[114:115], s[44:45]
	v_pk_mul_f32 v[116:117], v[116:117], s[44:45]
	v_pk_mul_f32 v[118:119], v[118:119], s[44:45]
	v_pk_mul_f32 v[120:121], v[120:121], s[44:45]
	v_pk_mul_f32 v[122:123], v[122:123], s[44:45]
	v_pk_mul_f32 v[124:125], v[124:125], s[44:45]
	v_pk_mul_f32 v[126:127], v[126:127], s[44:45]
	v_cvt_pk_fp8_f32 v8, v96, v100
	v_cvt_pk_fp8_f32 v9, v104, v108
	v_cvt_pk_fp8_f32 v10, v112, v116
	v_cvt_pk_fp8_f32 v11, v120, v124
	v_and_b32_e32 v8, 0xffff, v8
	v_and_b32_e32 v10, 0xffff, v10
	v_lshl_or_b32 v184, v9, 16, v8
	v_lshl_or_b32 v185, v11, 16, v10
	global_store_dwordx2 v170, v[184:185], s[76:77] sc1
	v_cvt_pk_fp8_f32 v8, v97, v101
	v_cvt_pk_fp8_f32 v9, v105, v109
	v_cvt_pk_fp8_f32 v10, v113, v117
	v_cvt_pk_fp8_f32 v11, v121, v125
	v_and_b32_e32 v8, 0xffff, v8
	v_and_b32_e32 v10, 0xffff, v10
	v_lshl_or_b32 v186, v9, 16, v8
	v_lshl_or_b32 v187, v11, 16, v10
	global_store_dwordx2 v171, v[186:187], s[76:77] sc1
	v_cvt_pk_fp8_f32 v8, v98, v102
	v_cvt_pk_fp8_f32 v9, v106, v110
	v_cvt_pk_fp8_f32 v10, v114, v118
	v_cvt_pk_fp8_f32 v11, v122, v126
	v_and_b32_e32 v8, 0xffff, v8
	v_and_b32_e32 v10, 0xffff, v10
	v_lshl_or_b32 v188, v9, 16, v8
	v_lshl_or_b32 v189, v11, 16, v10
	global_store_dwordx2 v172, v[188:189], s[76:77] sc1
	v_cvt_pk_fp8_f32 v8, v99, v103
	v_cvt_pk_fp8_f32 v9, v107, v111
	v_cvt_pk_fp8_f32 v10, v115, v119
	v_cvt_pk_fp8_f32 v11, v123, v127
	v_and_b32_e32 v8, 0xffff, v8
	v_and_b32_e32 v10, 0xffff, v10
	v_lshl_or_b32 v190, v9, 16, v8
	v_lshl_or_b32 v191, v11, 16, v10
	global_store_dwordx2 v173, v[190:191], s[76:77] sc1
	s_waitcnt vmcnt(16)
	v_pk_mul_f32 v[128:129], v[128:129], s[44:45]
	v_pk_mul_f32 v[130:131], v[130:131], s[44:45]
	v_pk_mul_f32 v[132:133], v[132:133], s[44:45]
	v_pk_mul_f32 v[134:135], v[134:135], s[44:45]
	v_pk_mul_f32 v[136:137], v[136:137], s[44:45]
	v_pk_mul_f32 v[138:139], v[138:139], s[44:45]
	v_pk_mul_f32 v[140:141], v[140:141], s[44:45]
	v_pk_mul_f32 v[142:143], v[142:143], s[44:45]
	v_pk_mul_f32 v[144:145], v[144:145], s[44:45]
	v_pk_mul_f32 v[146:147], v[146:147], s[44:45]
	v_pk_mul_f32 v[148:149], v[148:149], s[44:45]
	v_pk_mul_f32 v[150:151], v[150:151], s[44:45]
	v_pk_mul_f32 v[152:153], v[152:153], s[44:45]
	v_pk_mul_f32 v[154:155], v[154:155], s[44:45]
	v_pk_mul_f32 v[156:157], v[156:157], s[44:45]
	v_pk_mul_f32 v[158:159], v[158:159], s[44:45]
	v_cvt_pk_fp8_f32 v8, v128, v132
	v_cvt_pk_fp8_f32 v9, v136, v140
	v_cvt_pk_fp8_f32 v10, v144, v148
	v_cvt_pk_fp8_f32 v11, v152, v156
	v_and_b32_e32 v8, 0xffff, v8
	v_and_b32_e32 v10, 0xffff, v10
	v_lshl_or_b32 v176, v9, 16, v8
	v_lshl_or_b32 v177, v11, 16, v10
	global_store_dwordx2 v170, v[176:177], s[78:79] sc1
	v_cvt_pk_fp8_f32 v8, v129, v133
	v_cvt_pk_fp8_f32 v9, v137, v141
	v_cvt_pk_fp8_f32 v10, v145, v149
	v_cvt_pk_fp8_f32 v11, v153, v157
	v_and_b32_e32 v8, 0xffff, v8
	v_and_b32_e32 v10, 0xffff, v10
	v_lshl_or_b32 v178, v9, 16, v8
	v_lshl_or_b32 v179, v11, 16, v10
	global_store_dwordx2 v171, v[178:179], s[78:79] sc1
	v_cvt_pk_fp8_f32 v8, v130, v134
	v_cvt_pk_fp8_f32 v9, v138, v142
	v_cvt_pk_fp8_f32 v10, v146, v150
	v_cvt_pk_fp8_f32 v11, v154, v158
	v_and_b32_e32 v8, 0xffff, v8
	v_and_b32_e32 v10, 0xffff, v10
	v_lshl_or_b32 v180, v9, 16, v8
	v_lshl_or_b32 v181, v11, 16, v10
	global_store_dwordx2 v172, v[180:181], s[78:79] sc1
	v_cvt_pk_fp8_f32 v8, v131, v135
	v_cvt_pk_fp8_f32 v9, v139, v143
	v_cvt_pk_fp8_f32 v10, v147, v151
	v_cvt_pk_fp8_f32 v11, v155, v159
	v_and_b32_e32 v8, 0xffff, v8
	v_and_b32_e32 v10, 0xffff, v10
	v_lshl_or_b32 v182, v9, 16, v8
	v_lshl_or_b32 v183, v11, 16, v10
	global_store_dwordx2 v173, v[182:183], s[78:79] sc1
	s_waitcnt vmcnt(8)
	v_pk_mul_f32 v[64:65], v[64:65], s[44:45]
	v_pk_mul_f32 v[66:67], v[66:67], s[44:45]
	v_pk_mul_f32 v[68:69], v[68:69], s[44:45]
	v_pk_mul_f32 v[70:71], v[70:71], s[44:45]
	v_pk_mul_f32 v[72:73], v[72:73], s[44:45]
	v_pk_mul_f32 v[74:75], v[74:75], s[44:45]
	v_pk_mul_f32 v[76:77], v[76:77], s[44:45]
	v_pk_mul_f32 v[78:79], v[78:79], s[44:45]
	v_pk_mul_f32 v[80:81], v[80:81], s[44:45]
	v_pk_mul_f32 v[82:83], v[82:83], s[44:45]
	v_pk_mul_f32 v[84:85], v[84:85], s[44:45]
	v_pk_mul_f32 v[86:87], v[86:87], s[44:45]
	v_pk_mul_f32 v[88:89], v[88:89], s[44:45]
	v_pk_mul_f32 v[90:91], v[90:91], s[44:45]
	v_pk_mul_f32 v[92:93], v[92:93], s[44:45]
	v_pk_mul_f32 v[94:95], v[94:95], s[44:45]
	v_cvt_pk_fp8_f32 v8, v64, v68
	v_cvt_pk_fp8_f32 v9, v72, v76
	v_cvt_pk_fp8_f32 v10, v80, v84
	v_cvt_pk_fp8_f32 v11, v88, v92
	v_and_b32_e32 v8, 0xffff, v8
	v_and_b32_e32 v10, 0xffff, v10
	v_lshl_or_b32 v184, v9, 16, v8
	v_lshl_or_b32 v185, v11, 16, v10
	global_store_dwordx2 v170, v[184:185], s[74:75] sc1
	v_cvt_pk_fp8_f32 v8, v65, v69
	v_cvt_pk_fp8_f32 v9, v73, v77
	v_cvt_pk_fp8_f32 v10, v81, v85
	v_cvt_pk_fp8_f32 v11, v89, v93
	v_and_b32_e32 v8, 0xffff, v8
	v_and_b32_e32 v10, 0xffff, v10
	v_lshl_or_b32 v186, v9, 16, v8
	v_lshl_or_b32 v187, v11, 16, v10
	global_store_dwordx2 v171, v[186:187], s[74:75] sc1
	v_cvt_pk_fp8_f32 v8, v66, v70
	v_cvt_pk_fp8_f32 v9, v74, v78
	v_cvt_pk_fp8_f32 v10, v82, v86
	v_cvt_pk_fp8_f32 v11, v90, v94
	v_and_b32_e32 v8, 0xffff, v8
	v_and_b32_e32 v10, 0xffff, v10
	v_lshl_or_b32 v188, v9, 16, v8
	v_lshl_or_b32 v189, v11, 16, v10
	global_store_dwordx2 v172, v[188:189], s[74:75] sc1
	v_cvt_pk_fp8_f32 v8, v67, v71
	v_cvt_pk_fp8_f32 v9, v75, v79
	v_cvt_pk_fp8_f32 v10, v83, v87
	v_cvt_pk_fp8_f32 v11, v91, v95
	v_and_b32_e32 v8, 0xffff, v8
	v_and_b32_e32 v10, 0xffff, v10
	v_lshl_or_b32 v190, v9, 16, v8
	v_lshl_or_b32 v191, v11, 16, v10
	global_store_dwordx2 v173, v[190:191], s[74:75] sc1
